# K64 GEMM loops with DMA issue interleaved between MFMAs and without s_setprio toggles; dprep weight prefetch; RWKV steps re-emitted (bit-identical)
# speedup vs baseline: 1.0622x; 1.0148x over previous
.Lk1_loop:
	s_waitcnt vmcnt(0)
	s_barrier
	ds_read_b128 v[140:143], v136 offset:0
	ds_read_b128 v[188:191], v232 offset:32768
	ds_read_b128 v[204:207], v232 offset:36864
	ds_read_b128 v[164:167], v136 offset:4096
	ds_read_b128 v[144:147], v137 offset:0
	ds_read_b128 v[192:195], v233 offset:32768
	ds_read_b128 v[208:211], v233 offset:36864
	ds_read_b128 v[170:173], v137 offset:4096
	s_waitcnt lgkmcnt(6)
	v_mfma_f32_32x32x16_bf16 v[96:111], v[188:191], v[140:143], v[96:111]
	v_lshl_add_u64 v[246:247], v[132:133], 0, s[4:5]
	v_lshl_add_u64 v[246:247], v[246:247], 0, s[14:15]
	s_add_i32 m0, s32, 0xc000
	s_nop 0
	global_load_lds_dwordx4 v[246:247], off
	s_waitcnt lgkmcnt(5)
	v_mfma_f32_32x32x16_bf16 v[80:95], v[204:207], v[140:143], v[80:95]
	v_lshl_add_u64 v[248:249], v[134:135], 0, s[4:5]
	v_lshl_add_u64 v[248:249], v[248:249], 0, s[14:15]
	s_add_i32 m0, s32, 0xc400
	s_nop 0
	global_load_lds_dwordx4 v[248:249], off
	s_waitcnt lgkmcnt(4)
	v_mfma_f32_32x32x16_bf16 v[112:127], v[188:191], v[164:167], v[112:127]
	v_lshl_add_u64 v[246:247], v[132:133], 0, s[4:5]
	v_lshl_add_u64 v[246:247], v[246:247], 0, s[14:15]
	v_lshl_add_u64 v[246:247], v[246:247], 0, s[16:17]
	s_add_i32 m0, s32, 0xc800
	s_nop 0
	global_load_lds_dwordx4 v[246:247], off
	v_mfma_f32_32x32x16_bf16 v[64:79], v[204:207], v[164:167], v[64:79]
	v_lshl_add_u64 v[248:249], v[134:135], 0, s[4:5]
	v_lshl_add_u64 v[248:249], v[248:249], 0, s[14:15]
	v_lshl_add_u64 v[248:249], v[248:249], 0, s[16:17]
	s_add_i32 m0, s32, 0xcc00
	s_nop 0
	global_load_lds_dwordx4 v[248:249], off
	ds_read_b128 v[148:151], v138 offset:0
	ds_read_b128 v[196:199], v237 offset:32768
	ds_read_b128 v[238:241], v237 offset:36864
	ds_read_b128 v[180:183], v138 offset:4096
	s_waitcnt lgkmcnt(6)
	v_mfma_f32_32x32x16_bf16 v[96:111], v[192:195], v[144:147], v[96:111]
	v_lshl_add_u64 v[246:247], v[128:129], 0, s[6:7]
	s_add_i32 m0, s13, 0x4000
	s_nop 0
	global_load_lds_dwordx4 v[246:247], off
	s_waitcnt lgkmcnt(5)
	v_mfma_f32_32x32x16_bf16 v[80:95], v[208:211], v[144:147], v[80:95]
	v_lshl_add_u64 v[248:249], v[130:131], 0, s[6:7]
	s_add_i32 m0, s13, 0x4400
	s_nop 0
	global_load_lds_dwordx4 v[248:249], off
	s_waitcnt lgkmcnt(4)
	v_mfma_f32_32x32x16_bf16 v[112:127], v[192:195], v[170:173], v[112:127]
	v_mfma_f32_32x32x16_bf16 v[64:79], v[208:211], v[170:173], v[64:79]
	ds_read_b128 v[160:163], v139 offset:0
	ds_read_b128 v[200:203], v252 offset:32768
	ds_read_b128 v[242:245], v252 offset:36864
	ds_read_b128 v[184:187], v139 offset:4096
	s_waitcnt lgkmcnt(6)
	v_mfma_f32_32x32x16_bf16 v[96:111], v[196:199], v[148:151], v[96:111]
	s_waitcnt lgkmcnt(5)
	v_mfma_f32_32x32x16_bf16 v[80:95], v[238:241], v[148:151], v[80:95]
	s_waitcnt lgkmcnt(4)
	v_mfma_f32_32x32x16_bf16 v[112:127], v[196:199], v[180:183], v[112:127]
	v_mfma_f32_32x32x16_bf16 v[64:79], v[238:241], v[180:183], v[64:79]
	s_waitcnt lgkmcnt(2)
	v_mfma_f32_32x32x16_bf16 v[96:111], v[200:203], v[160:163], v[96:111]
	s_waitcnt lgkmcnt(1)
	v_mfma_f32_32x32x16_bf16 v[80:95], v[242:245], v[160:163], v[80:95]
	s_waitcnt lgkmcnt(0)
	v_mfma_f32_32x32x16_bf16 v[112:127], v[200:203], v[184:187], v[112:127]
	v_mfma_f32_32x32x16_bf16 v[64:79], v[242:245], v[184:187], v[64:79]
	s_waitcnt vmcnt(2)
	s_barrier
	ds_read_b128 v[188:191], v232 offset:49152
	ds_read_b128 v[204:207], v232 offset:53248
	ds_read_b128 v[192:195], v233 offset:49152
	ds_read_b128 v[208:211], v233 offset:53248
	ds_read_b128 v[196:199], v237 offset:49152
	ds_read_b128 v[238:241], v237 offset:53248
	ds_read_b128 v[200:203], v252 offset:49152
	ds_read_b128 v[242:245], v252 offset:53248
	s_waitcnt lgkmcnt(7)
	v_mfma_f32_32x32x16_bf16 v[48:63], v[188:191], v[140:143], v[48:63]
	v_lshl_add_u64 v[246:247], v[132:133], 0, s[6:7]
	s_add_i32 m0, s32, 0x8000
	s_nop 0
	global_load_lds_dwordx4 v[246:247], off
	s_waitcnt lgkmcnt(6)
	v_mfma_f32_32x32x16_bf16 v[16:31], v[204:207], v[140:143], v[16:31]
	v_lshl_add_u64 v[248:249], v[134:135], 0, s[6:7]
	s_add_i32 m0, s32, 0x8400
	s_nop 0
	global_load_lds_dwordx4 v[248:249], off
	v_mfma_f32_32x32x16_bf16 v[32:47], v[188:191], v[164:167], v[32:47]
	v_lshl_add_u64 v[246:247], v[132:133], 0, s[6:7]
	v_lshl_add_u64 v[246:247], v[246:247], 0, s[16:17]
	s_add_i32 m0, s32, 0x8800
	s_nop 0
	global_load_lds_dwordx4 v[246:247], off
	v_mfma_f32_32x32x16_bf16 v[0:15], v[204:207], v[164:167], v[0:15]
	v_lshl_add_u64 v[248:249], v[134:135], 0, s[6:7]
	v_lshl_add_u64 v[248:249], v[248:249], 0, s[16:17]
	s_add_i32 m0, s32, 0x8c00
	s_nop 0
	global_load_lds_dwordx4 v[248:249], off
	s_waitcnt lgkmcnt(5)
	v_mfma_f32_32x32x16_bf16 v[48:63], v[192:195], v[144:147], v[48:63]
	v_lshl_add_u64 v[246:247], v[128:129], 0, s[6:7]
	v_lshl_add_u64 v[246:247], v[246:247], 0, s[14:15]
	s_add_i32 m0, s13, 0x6000
	s_nop 0
	global_load_lds_dwordx4 v[246:247], off
	s_waitcnt lgkmcnt(4)
	v_mfma_f32_32x32x16_bf16 v[16:31], v[208:211], v[144:147], v[16:31]
	v_lshl_add_u64 v[248:249], v[130:131], 0, s[6:7]
	v_lshl_add_u64 v[248:249], v[248:249], 0, s[14:15]
	s_add_i32 m0, s13, 0x6400
	s_nop 0
	global_load_lds_dwordx4 v[248:249], off
	s_add_u32 s4, s4, 0x80
	s_addc_u32 s5, s5, 0
	s_add_u32 s6, s6, 0x80
	s_addc_u32 s7, s7, 0
	v_mfma_f32_32x32x16_bf16 v[32:47], v[192:195], v[170:173], v[32:47]
	v_mfma_f32_32x32x16_bf16 v[0:15], v[208:211], v[170:173], v[0:15]
	s_waitcnt lgkmcnt(3)
	v_mfma_f32_32x32x16_bf16 v[48:63], v[196:199], v[148:151], v[48:63]
	s_waitcnt lgkmcnt(2)
	v_mfma_f32_32x32x16_bf16 v[16:31], v[238:241], v[148:151], v[16:31]
	v_mfma_f32_32x32x16_bf16 v[32:47], v[196:199], v[180:183], v[32:47]
	v_mfma_f32_32x32x16_bf16 v[0:15], v[238:241], v[180:183], v[0:15]
	s_waitcnt lgkmcnt(1)
	v_mfma_f32_32x32x16_bf16 v[48:63], v[200:203], v[160:163], v[48:63]
	s_waitcnt lgkmcnt(0)
	v_mfma_f32_32x32x16_bf16 v[16:31], v[242:245], v[160:163], v[16:31]
	v_mfma_f32_32x32x16_bf16 v[32:47], v[200:203], v[184:187], v[32:47]
	v_mfma_f32_32x32x16_bf16 v[0:15], v[242:245], v[184:187], v[0:15]
	s_waitcnt vmcnt(0)
	s_barrier
	ds_read_b128 v[140:143], v136 offset:16384
	ds_read_b128 v[188:191], v232 offset:32768
	ds_read_b128 v[204:207], v232 offset:36864
	ds_read_b128 v[164:167], v136 offset:20480
	ds_read_b128 v[144:147], v137 offset:16384
	ds_read_b128 v[192:195], v233 offset:32768
	ds_read_b128 v[208:211], v233 offset:36864
	ds_read_b128 v[170:173], v137 offset:20480
	s_waitcnt lgkmcnt(6)
	v_mfma_f32_32x32x16_bf16 v[96:111], v[188:191], v[140:143], v[96:111]
	v_lshl_add_u64 v[246:247], v[132:133], 0, s[4:5]
	v_lshl_add_u64 v[246:247], v[246:247], 0, s[14:15]
	s_add_i32 m0, s32, 0xc000
	s_nop 0
	global_load_lds_dwordx4 v[246:247], off
	s_waitcnt lgkmcnt(5)
	v_mfma_f32_32x32x16_bf16 v[80:95], v[204:207], v[140:143], v[80:95]
	v_lshl_add_u64 v[248:249], v[134:135], 0, s[4:5]
	v_lshl_add_u64 v[248:249], v[248:249], 0, s[14:15]
	s_add_i32 m0, s32, 0xc400
	s_nop 0
	global_load_lds_dwordx4 v[248:249], off
	s_waitcnt lgkmcnt(4)
	v_mfma_f32_32x32x16_bf16 v[112:127], v[188:191], v[164:167], v[112:127]
	v_lshl_add_u64 v[246:247], v[132:133], 0, s[4:5]
	v_lshl_add_u64 v[246:247], v[246:247], 0, s[14:15]
	v_lshl_add_u64 v[246:247], v[246:247], 0, s[16:17]
	s_add_i32 m0, s32, 0xc800
	s_nop 0
	global_load_lds_dwordx4 v[246:247], off
	v_mfma_f32_32x32x16_bf16 v[64:79], v[204:207], v[164:167], v[64:79]
	v_lshl_add_u64 v[248:249], v[134:135], 0, s[4:5]
	v_lshl_add_u64 v[248:249], v[248:249], 0, s[14:15]
	v_lshl_add_u64 v[248:249], v[248:249], 0, s[16:17]
	s_add_i32 m0, s32, 0xcc00
	s_nop 0
	global_load_lds_dwordx4 v[248:249], off
	ds_read_b128 v[148:151], v138 offset:16384
	ds_read_b128 v[196:199], v237 offset:32768
	ds_read_b128 v[238:241], v237 offset:36864
	ds_read_b128 v[180:183], v138 offset:20480
	s_waitcnt lgkmcnt(6)
	v_mfma_f32_32x32x16_bf16 v[96:111], v[192:195], v[144:147], v[96:111]
	v_lshl_add_u64 v[246:247], v[128:129], 0, s[6:7]
	s_add_i32 m0, s13, 0x0
	s_nop 0
	global_load_lds_dwordx4 v[246:247], off
	s_waitcnt lgkmcnt(5)
	v_mfma_f32_32x32x16_bf16 v[80:95], v[208:211], v[144:147], v[80:95]
	v_lshl_add_u64 v[248:249], v[130:131], 0, s[6:7]
	s_add_i32 m0, s13, 0x400
	s_nop 0
	global_load_lds_dwordx4 v[248:249], off
	s_waitcnt lgkmcnt(4)
	v_mfma_f32_32x32x16_bf16 v[112:127], v[192:195], v[170:173], v[112:127]
	v_mfma_f32_32x32x16_bf16 v[64:79], v[208:211], v[170:173], v[64:79]
	ds_read_b128 v[160:163], v139 offset:16384
	ds_read_b128 v[200:203], v252 offset:32768
	ds_read_b128 v[242:245], v252 offset:36864
	ds_read_b128 v[184:187], v139 offset:20480
	s_waitcnt lgkmcnt(6)
	v_mfma_f32_32x32x16_bf16 v[96:111], v[196:199], v[148:151], v[96:111]
	s_waitcnt lgkmcnt(5)
	v_mfma_f32_32x32x16_bf16 v[80:95], v[238:241], v[148:151], v[80:95]
	s_waitcnt lgkmcnt(4)
	v_mfma_f32_32x32x16_bf16 v[112:127], v[196:199], v[180:183], v[112:127]
	v_mfma_f32_32x32x16_bf16 v[64:79], v[238:241], v[180:183], v[64:79]
	s_waitcnt lgkmcnt(2)
	v_mfma_f32_32x32x16_bf16 v[96:111], v[200:203], v[160:163], v[96:111]
	s_waitcnt lgkmcnt(1)
	v_mfma_f32_32x32x16_bf16 v[80:95], v[242:245], v[160:163], v[80:95]
	s_waitcnt lgkmcnt(0)
	v_mfma_f32_32x32x16_bf16 v[112:127], v[200:203], v[184:187], v[112:127]
	v_mfma_f32_32x32x16_bf16 v[64:79], v[242:245], v[184:187], v[64:79]
	s_waitcnt vmcnt(2)
	s_barrier
	ds_read_b128 v[188:191], v232 offset:49152
	ds_read_b128 v[204:207], v232 offset:53248
	ds_read_b128 v[192:195], v233 offset:49152
	ds_read_b128 v[208:211], v233 offset:53248
	ds_read_b128 v[196:199], v237 offset:49152
	ds_read_b128 v[238:241], v237 offset:53248
	ds_read_b128 v[200:203], v252 offset:49152
	ds_read_b128 v[242:245], v252 offset:53248
	s_waitcnt lgkmcnt(7)
	v_mfma_f32_32x32x16_bf16 v[48:63], v[188:191], v[140:143], v[48:63]
	v_lshl_add_u64 v[246:247], v[132:133], 0, s[6:7]
	s_add_i32 m0, s32, 0x8000
	s_nop 0
	global_load_lds_dwordx4 v[246:247], off
	s_waitcnt lgkmcnt(6)
	v_mfma_f32_32x32x16_bf16 v[16:31], v[204:207], v[140:143], v[16:31]
	v_lshl_add_u64 v[248:249], v[134:135], 0, s[6:7]
	s_add_i32 m0, s32, 0x8400
	s_nop 0
	global_load_lds_dwordx4 v[248:249], off
	v_mfma_f32_32x32x16_bf16 v[32:47], v[188:191], v[164:167], v[32:47]
	v_lshl_add_u64 v[246:247], v[132:133], 0, s[6:7]
	v_lshl_add_u64 v[246:247], v[246:247], 0, s[16:17]
	s_add_i32 m0, s32, 0x8800
	s_nop 0
	global_load_lds_dwordx4 v[246:247], off
	v_mfma_f32_32x32x16_bf16 v[0:15], v[204:207], v[164:167], v[0:15]
	v_lshl_add_u64 v[248:249], v[134:135], 0, s[6:7]
	v_lshl_add_u64 v[248:249], v[248:249], 0, s[16:17]
	s_add_i32 m0, s32, 0x8c00
	s_nop 0
	global_load_lds_dwordx4 v[248:249], off
	s_waitcnt lgkmcnt(5)
	v_mfma_f32_32x32x16_bf16 v[48:63], v[192:195], v[144:147], v[48:63]
	v_lshl_add_u64 v[246:247], v[128:129], 0, s[6:7]
	v_lshl_add_u64 v[246:247], v[246:247], 0, s[14:15]
	s_add_i32 m0, s13, 0x2000
	s_nop 0
	global_load_lds_dwordx4 v[246:247], off
	s_waitcnt lgkmcnt(4)
	v_mfma_f32_32x32x16_bf16 v[16:31], v[208:211], v[144:147], v[16:31]
	v_lshl_add_u64 v[248:249], v[130:131], 0, s[6:7]
	v_lshl_add_u64 v[248:249], v[248:249], 0, s[14:15]
	s_add_i32 m0, s13, 0x2400
	s_nop 0
	global_load_lds_dwordx4 v[248:249], off
	s_add_u32 s4, s4, 0x80
	s_addc_u32 s5, s5, 0
	s_add_u32 s6, s6, 0x80
	s_addc_u32 s7, s7, 0
	v_mfma_f32_32x32x16_bf16 v[32:47], v[192:195], v[170:173], v[32:47]
	v_mfma_f32_32x32x16_bf16 v[0:15], v[208:211], v[170:173], v[0:15]
	s_waitcnt lgkmcnt(3)
	v_mfma_f32_32x32x16_bf16 v[48:63], v[196:199], v[148:151], v[48:63]
	s_waitcnt lgkmcnt(2)
	v_mfma_f32_32x32x16_bf16 v[16:31], v[238:241], v[148:151], v[16:31]
	v_mfma_f32_32x32x16_bf16 v[32:47], v[196:199], v[180:183], v[32:47]
	v_mfma_f32_32x32x16_bf16 v[0:15], v[238:241], v[180:183], v[0:15]
	s_waitcnt lgkmcnt(1)
	v_mfma_f32_32x32x16_bf16 v[48:63], v[200:203], v[160:163], v[48:63]
	s_waitcnt lgkmcnt(0)
	v_mfma_f32_32x32x16_bf16 v[16:31], v[242:245], v[160:163], v[16:31]
	v_mfma_f32_32x32x16_bf16 v[32:47], v[200:203], v[184:187], v[32:47]
	v_mfma_f32_32x32x16_bf16 v[0:15], v[242:245], v[184:187], v[0:15]
	s_add_i32 s37, s37, -1
	s_cmp_lg_u32 s37, 0
	s_cbranch_scc1 .Lk1_loop
	s_waitcnt vmcnt(0)
	s_barrier
	ds_read_b128 v[140:143], v136 offset:0
	ds_read_b128 v[188:191], v232 offset:32768
	ds_read_b128 v[204:207], v232 offset:36864
	ds_read_b128 v[164:167], v136 offset:4096
	ds_read_b128 v[144:147], v137 offset:0
	ds_read_b128 v[192:195], v233 offset:32768
	ds_read_b128 v[208:211], v233 offset:36864
	ds_read_b128 v[170:173], v137 offset:4096
	s_waitcnt lgkmcnt(6)
	v_mfma_f32_32x32x16_bf16 v[96:111], v[188:191], v[140:143], v[96:111]
	v_lshl_add_u64 v[246:247], v[132:133], 0, s[4:5]
	v_lshl_add_u64 v[246:247], v[246:247], 0, s[14:15]
	s_add_i32 m0, s32, 0xc000
	s_nop 0
	global_load_lds_dwordx4 v[246:247], off
	s_waitcnt lgkmcnt(5)
	v_mfma_f32_32x32x16_bf16 v[80:95], v[204:207], v[140:143], v[80:95]
	v_lshl_add_u64 v[248:249], v[134:135], 0, s[4:5]
	v_lshl_add_u64 v[248:249], v[248:249], 0, s[14:15]
	s_add_i32 m0, s32, 0xc400
	s_nop 0
	global_load_lds_dwordx4 v[248:249], off
	s_waitcnt lgkmcnt(4)
	v_mfma_f32_32x32x16_bf16 v[112:127], v[188:191], v[164:167], v[112:127]
	v_lshl_add_u64 v[246:247], v[132:133], 0, s[4:5]
	v_lshl_add_u64 v[246:247], v[246:247], 0, s[14:15]
	v_lshl_add_u64 v[246:247], v[246:247], 0, s[16:17]
	s_add_i32 m0, s32, 0xc800
	s_nop 0
	global_load_lds_dwordx4 v[246:247], off
	v_mfma_f32_32x32x16_bf16 v[64:79], v[204:207], v[164:167], v[64:79]
	v_lshl_add_u64 v[248:249], v[134:135], 0, s[4:5]
	v_lshl_add_u64 v[248:249], v[248:249], 0, s[14:15]
	v_lshl_add_u64 v[248:249], v[248:249], 0, s[16:17]
	s_add_i32 m0, s32, 0xcc00
	s_nop 0
	global_load_lds_dwordx4 v[248:249], off
	ds_read_b128 v[148:151], v138 offset:0
	ds_read_b128 v[196:199], v237 offset:32768
	ds_read_b128 v[238:241], v237 offset:36864
	ds_read_b128 v[180:183], v138 offset:4096
	s_waitcnt lgkmcnt(6)
	v_mfma_f32_32x32x16_bf16 v[96:111], v[192:195], v[144:147], v[96:111]
	v_lshl_add_u64 v[246:247], v[128:129], 0, s[6:7]
	s_add_i32 m0, s13, 0x4000
	s_nop 0
	global_load_lds_dwordx4 v[246:247], off
	s_waitcnt lgkmcnt(5)
	v_mfma_f32_32x32x16_bf16 v[80:95], v[208:211], v[144:147], v[80:95]
	v_lshl_add_u64 v[248:249], v[130:131], 0, s[6:7]
	s_add_i32 m0, s13, 0x4400
	s_nop 0
	global_load_lds_dwordx4 v[248:249], off
	s_waitcnt lgkmcnt(4)
	v_mfma_f32_32x32x16_bf16 v[112:127], v[192:195], v[170:173], v[112:127]
	v_mfma_f32_32x32x16_bf16 v[64:79], v[208:211], v[170:173], v[64:79]
	ds_read_b128 v[160:163], v139 offset:0
	ds_read_b128 v[200:203], v252 offset:32768
	ds_read_b128 v[242:245], v252 offset:36864
	ds_read_b128 v[184:187], v139 offset:4096
	s_waitcnt lgkmcnt(6)
	v_mfma_f32_32x32x16_bf16 v[96:111], v[196:199], v[148:151], v[96:111]
	s_waitcnt lgkmcnt(5)
	v_mfma_f32_32x32x16_bf16 v[80:95], v[238:241], v[148:151], v[80:95]
	s_waitcnt lgkmcnt(4)
	v_mfma_f32_32x32x16_bf16 v[112:127], v[196:199], v[180:183], v[112:127]
	v_mfma_f32_32x32x16_bf16 v[64:79], v[238:241], v[180:183], v[64:79]
	s_waitcnt lgkmcnt(2)
	v_mfma_f32_32x32x16_bf16 v[96:111], v[200:203], v[160:163], v[96:111]
	s_waitcnt lgkmcnt(1)
	v_mfma_f32_32x32x16_bf16 v[80:95], v[242:245], v[160:163], v[80:95]
	s_waitcnt lgkmcnt(0)
	v_mfma_f32_32x32x16_bf16 v[112:127], v[200:203], v[184:187], v[112:127]
	v_mfma_f32_32x32x16_bf16 v[64:79], v[242:245], v[184:187], v[64:79]
	s_waitcnt vmcnt(2)
	s_barrier
	ds_read_b128 v[188:191], v232 offset:49152
	ds_read_b128 v[204:207], v232 offset:53248
	ds_read_b128 v[192:195], v233 offset:49152
	ds_read_b128 v[208:211], v233 offset:53248
	ds_read_b128 v[196:199], v237 offset:49152
	ds_read_b128 v[238:241], v237 offset:53248
	ds_read_b128 v[200:203], v252 offset:49152
	ds_read_b128 v[242:245], v252 offset:53248
	s_waitcnt lgkmcnt(7)
	v_mfma_f32_32x32x16_bf16 v[48:63], v[188:191], v[140:143], v[48:63]
	v_lshl_add_u64 v[246:247], v[132:133], 0, s[6:7]
	s_add_i32 m0, s32, 0x8000
	s_nop 0
	global_load_lds_dwordx4 v[246:247], off
	s_waitcnt lgkmcnt(6)
	v_mfma_f32_32x32x16_bf16 v[16:31], v[204:207], v[140:143], v[16:31]
	v_lshl_add_u64 v[248:249], v[134:135], 0, s[6:7]
	s_add_i32 m0, s32, 0x8400
	s_nop 0
	global_load_lds_dwordx4 v[248:249], off
	v_mfma_f32_32x32x16_bf16 v[32:47], v[188:191], v[164:167], v[32:47]
	v_lshl_add_u64 v[246:247], v[132:133], 0, s[6:7]
	v_lshl_add_u64 v[246:247], v[246:247], 0, s[16:17]
	s_add_i32 m0, s32, 0x8800
	s_nop 0
	global_load_lds_dwordx4 v[246:247], off
	v_mfma_f32_32x32x16_bf16 v[0:15], v[204:207], v[164:167], v[0:15]
	v_lshl_add_u64 v[248:249], v[134:135], 0, s[6:7]
	v_lshl_add_u64 v[248:249], v[248:249], 0, s[16:17]
	s_add_i32 m0, s32, 0x8c00
	s_nop 0
	global_load_lds_dwordx4 v[248:249], off
	s_waitcnt lgkmcnt(5)
	v_mfma_f32_32x32x16_bf16 v[48:63], v[192:195], v[144:147], v[48:63]
	v_lshl_add_u64 v[246:247], v[128:129], 0, s[6:7]
	v_lshl_add_u64 v[246:247], v[246:247], 0, s[14:15]
	s_add_i32 m0, s13, 0x6000
	s_nop 0
	global_load_lds_dwordx4 v[246:247], off
	s_waitcnt lgkmcnt(4)
	v_mfma_f32_32x32x16_bf16 v[16:31], v[208:211], v[144:147], v[16:31]
	v_lshl_add_u64 v[248:249], v[130:131], 0, s[6:7]
	v_lshl_add_u64 v[248:249], v[248:249], 0, s[14:15]
	s_add_i32 m0, s13, 0x6400
	s_nop 0
	global_load_lds_dwordx4 v[248:249], off
	s_add_u32 s4, s4, 0x80
	s_addc_u32 s5, s5, 0
	s_add_u32 s6, s6, 0x80
	s_addc_u32 s7, s7, 0
	v_mfma_f32_32x32x16_bf16 v[32:47], v[192:195], v[170:173], v[32:47]
	v_mfma_f32_32x32x16_bf16 v[0:15], v[208:211], v[170:173], v[0:15]
	s_waitcnt lgkmcnt(3)
	v_mfma_f32_32x32x16_bf16 v[48:63], v[196:199], v[148:151], v[48:63]
	s_waitcnt lgkmcnt(2)
	v_mfma_f32_32x32x16_bf16 v[16:31], v[238:241], v[148:151], v[16:31]
	v_mfma_f32_32x32x16_bf16 v[32:47], v[196:199], v[180:183], v[32:47]
	v_mfma_f32_32x32x16_bf16 v[0:15], v[238:241], v[180:183], v[0:15]
	s_waitcnt lgkmcnt(1)
	v_mfma_f32_32x32x16_bf16 v[48:63], v[200:203], v[160:163], v[48:63]
	s_waitcnt lgkmcnt(0)
	v_mfma_f32_32x32x16_bf16 v[16:31], v[242:245], v[160:163], v[16:31]
	v_mfma_f32_32x32x16_bf16 v[32:47], v[200:203], v[184:187], v[32:47]
	v_mfma_f32_32x32x16_bf16 v[0:15], v[242:245], v[184:187], v[0:15]
	s_waitcnt vmcnt(0)
	s_barrier
	ds_read_b128 v[140:143], v136 offset:16384
	ds_read_b128 v[188:191], v232 offset:32768
	ds_read_b128 v[204:207], v232 offset:36864
	ds_read_b128 v[164:167], v136 offset:20480
	ds_read_b128 v[144:147], v137 offset:16384
	ds_read_b128 v[192:195], v233 offset:32768
	ds_read_b128 v[208:211], v233 offset:36864
	ds_read_b128 v[170:173], v137 offset:20480
	s_waitcnt lgkmcnt(6)
	v_mfma_f32_32x32x16_bf16 v[96:111], v[188:191], v[140:143], v[96:111]
	v_lshl_add_u64 v[246:247], v[132:133], 0, s[4:5]
	v_lshl_add_u64 v[246:247], v[246:247], 0, s[14:15]
	s_add_i32 m0, s32, 0xc000
	s_nop 0
	global_load_lds_dwordx4 v[246:247], off
	s_waitcnt lgkmcnt(5)
	v_mfma_f32_32x32x16_bf16 v[80:95], v[204:207], v[140:143], v[80:95]
	v_lshl_add_u64 v[248:249], v[134:135], 0, s[4:5]
	v_lshl_add_u64 v[248:249], v[248:249], 0, s[14:15]
	s_add_i32 m0, s32, 0xc400
	s_nop 0
	global_load_lds_dwordx4 v[248:249], off
	s_waitcnt lgkmcnt(4)
	v_mfma_f32_32x32x16_bf16 v[112:127], v[188:191], v[164:167], v[112:127]
	v_lshl_add_u64 v[246:247], v[132:133], 0, s[4:5]
	v_lshl_add_u64 v[246:247], v[246:247], 0, s[14:15]
	v_lshl_add_u64 v[246:247], v[246:247], 0, s[16:17]
	s_add_i32 m0, s32, 0xc800
	s_nop 0
	global_load_lds_dwordx4 v[246:247], off
	v_mfma_f32_32x32x16_bf16 v[64:79], v[204:207], v[164:167], v[64:79]
	v_lshl_add_u64 v[248:249], v[134:135], 0, s[4:5]
	v_lshl_add_u64 v[248:249], v[248:249], 0, s[14:15]
	v_lshl_add_u64 v[248:249], v[248:249], 0, s[16:17]
	s_add_i32 m0, s32, 0xcc00
	s_nop 0
	global_load_lds_dwordx4 v[248:249], off
	ds_read_b128 v[148:151], v138 offset:16384
	ds_read_b128 v[196:199], v237 offset:32768
	ds_read_b128 v[238:241], v237 offset:36864
	ds_read_b128 v[180:183], v138 offset:20480
	s_waitcnt lgkmcnt(6)
	v_mfma_f32_32x32x16_bf16 v[96:111], v[192:195], v[144:147], v[96:111]
	s_waitcnt lgkmcnt(5)
	v_mfma_f32_32x32x16_bf16 v[80:95], v[208:211], v[144:147], v[80:95]
	s_waitcnt lgkmcnt(4)
	v_mfma_f32_32x32x16_bf16 v[112:127], v[192:195], v[170:173], v[112:127]
	v_mfma_f32_32x32x16_bf16 v[64:79], v[208:211], v[170:173], v[64:79]
	ds_read_b128 v[160:163], v139 offset:16384
	ds_read_b128 v[200:203], v252 offset:32768
	ds_read_b128 v[242:245], v252 offset:36864
	ds_read_b128 v[184:187], v139 offset:20480
	s_waitcnt lgkmcnt(6)
	v_mfma_f32_32x32x16_bf16 v[96:111], v[196:199], v[148:151], v[96:111]
	s_waitcnt lgkmcnt(5)
	v_mfma_f32_32x32x16_bf16 v[80:95], v[238:241], v[148:151], v[80:95]
	s_waitcnt lgkmcnt(4)
	v_mfma_f32_32x32x16_bf16 v[112:127], v[196:199], v[180:183], v[112:127]
	v_mfma_f32_32x32x16_bf16 v[64:79], v[238:241], v[180:183], v[64:79]
	s_waitcnt lgkmcnt(2)
	v_mfma_f32_32x32x16_bf16 v[96:111], v[200:203], v[160:163], v[96:111]
	s_waitcnt lgkmcnt(1)
	v_mfma_f32_32x32x16_bf16 v[80:95], v[242:245], v[160:163], v[80:95]
	s_waitcnt lgkmcnt(0)
	v_mfma_f32_32x32x16_bf16 v[112:127], v[200:203], v[184:187], v[112:127]
	v_mfma_f32_32x32x16_bf16 v[64:79], v[242:245], v[184:187], v[64:79]
	s_waitcnt vmcnt(0)
	s_barrier
	ds_read_b128 v[188:191], v232 offset:49152
	ds_read_b128 v[204:207], v232 offset:53248
	ds_read_b128 v[192:195], v233 offset:49152
	ds_read_b128 v[208:211], v233 offset:53248
	ds_read_b128 v[196:199], v237 offset:49152
	ds_read_b128 v[238:241], v237 offset:53248
	ds_read_b128 v[200:203], v252 offset:49152
	ds_read_b128 v[242:245], v252 offset:53248
	s_waitcnt lgkmcnt(7)
	v_mfma_f32_32x32x16_bf16 v[48:63], v[188:191], v[140:143], v[48:63]
	s_waitcnt lgkmcnt(6)
	v_mfma_f32_32x32x16_bf16 v[16:31], v[204:207], v[140:143], v[16:31]
	v_mfma_f32_32x32x16_bf16 v[32:47], v[188:191], v[164:167], v[32:47]
	v_mfma_f32_32x32x16_bf16 v[0:15], v[204:207], v[164:167], v[0:15]
	s_waitcnt lgkmcnt(5)
	v_mfma_f32_32x32x16_bf16 v[48:63], v[192:195], v[144:147], v[48:63]
	s_waitcnt lgkmcnt(4)
	v_mfma_f32_32x32x16_bf16 v[16:31], v[208:211], v[144:147], v[16:31]
	v_mfma_f32_32x32x16_bf16 v[32:47], v[192:195], v[170:173], v[32:47]
	v_mfma_f32_32x32x16_bf16 v[0:15], v[208:211], v[170:173], v[0:15]
	s_waitcnt lgkmcnt(3)
	v_mfma_f32_32x32x16_bf16 v[48:63], v[196:199], v[148:151], v[48:63]
	s_waitcnt lgkmcnt(2)
	v_mfma_f32_32x32x16_bf16 v[16:31], v[238:241], v[148:151], v[16:31]
	v_mfma_f32_32x32x16_bf16 v[32:47], v[196:199], v[180:183], v[32:47]
	v_mfma_f32_32x32x16_bf16 v[0:15], v[238:241], v[180:183], v[0:15]
	s_waitcnt lgkmcnt(1)
	v_mfma_f32_32x32x16_bf16 v[48:63], v[200:203], v[160:163], v[48:63]
	s_waitcnt lgkmcnt(0)
	v_mfma_f32_32x32x16_bf16 v[16:31], v[242:245], v[160:163], v[16:31]
	v_mfma_f32_32x32x16_bf16 v[32:47], v[200:203], v[184:187], v[32:47]
	v_mfma_f32_32x32x16_bf16 v[0:15], v[242:245], v[184:187], v[0:15]

.Lk4_loop:
	s_waitcnt vmcnt(0)
	s_barrier
	ds_read_b128 v[140:143], v136 offset:0
	ds_read_b128 v[188:191], v232 offset:32768
	ds_read_b128 v[204:207], v232 offset:36864
	ds_read_b128 v[164:167], v136 offset:4096
	ds_read_b128 v[144:147], v137 offset:0
	ds_read_b128 v[192:195], v233 offset:32768
	ds_read_b128 v[208:211], v233 offset:36864
	ds_read_b128 v[170:173], v137 offset:4096
	s_waitcnt lgkmcnt(6)
	v_mfma_f32_32x32x16_bf16 v[64:79], v[188:191], v[140:143], v[64:79]
	v_lshl_add_u64 v[246:247], v[132:133], 0, s[48:49]
	v_lshl_add_u64 v[246:247], v[246:247], 0, s[52:53]
	s_add_i32 m0, s4, 0xc000
	s_nop 0
	global_load_lds_dwordx4 v[246:247], off
	s_waitcnt lgkmcnt(5)
	v_mfma_f32_32x32x16_bf16 v[80:95], v[204:207], v[140:143], v[80:95]
	v_lshl_add_u64 v[248:249], v[134:135], 0, s[48:49]
	v_lshl_add_u64 v[248:249], v[248:249], 0, s[52:53]
	s_add_i32 m0, s4, 0xc400
	s_nop 0
	global_load_lds_dwordx4 v[248:249], off
	s_waitcnt lgkmcnt(4)
	v_mfma_f32_32x32x16_bf16 v[112:127], v[188:191], v[164:167], v[112:127]
	v_lshl_add_u64 v[246:247], v[132:133], 0, s[48:49]
	v_lshl_add_u64 v[246:247], v[246:247], 0, s[52:53]
	v_lshl_add_u64 v[246:247], v[246:247], 0, s[54:55]
	s_add_i32 m0, s4, 0xc800
	s_nop 0
	global_load_lds_dwordx4 v[246:247], off
	v_mfma_f32_32x32x16_bf16 v[96:111], v[204:207], v[164:167], v[96:111]
	v_lshl_add_u64 v[248:249], v[134:135], 0, s[48:49]
	v_lshl_add_u64 v[248:249], v[248:249], 0, s[52:53]
	v_lshl_add_u64 v[248:249], v[248:249], 0, s[54:55]
	s_add_i32 m0, s4, 0xcc00
	s_nop 0
	global_load_lds_dwordx4 v[248:249], off
	ds_read_b128 v[148:151], v138 offset:0
	ds_read_b128 v[196:199], v237 offset:32768
	ds_read_b128 v[238:241], v237 offset:36864
	ds_read_b128 v[180:183], v138 offset:4096
	s_waitcnt lgkmcnt(6)
	v_mfma_f32_32x32x16_bf16 v[64:79], v[192:195], v[144:147], v[64:79]
	v_lshl_add_u64 v[246:247], v[128:129], 0, s[50:51]
	s_add_i32 m0, s63, 0x4000
	s_nop 0
	global_load_lds_dwordx4 v[246:247], off
	s_waitcnt lgkmcnt(5)
	v_mfma_f32_32x32x16_bf16 v[80:95], v[208:211], v[144:147], v[80:95]
	v_lshl_add_u64 v[248:249], v[130:131], 0, s[50:51]
	s_add_i32 m0, s63, 0x4400
	s_nop 0
	global_load_lds_dwordx4 v[248:249], off
	s_waitcnt lgkmcnt(4)
	v_mfma_f32_32x32x16_bf16 v[112:127], v[192:195], v[170:173], v[112:127]
	v_mfma_f32_32x32x16_bf16 v[96:111], v[208:211], v[170:173], v[96:111]
	ds_read_b128 v[160:163], v139 offset:0
	ds_read_b128 v[200:203], v252 offset:32768
	ds_read_b128 v[242:245], v252 offset:36864
	ds_read_b128 v[184:187], v139 offset:4096
	s_waitcnt lgkmcnt(6)
	v_mfma_f32_32x32x16_bf16 v[64:79], v[196:199], v[148:151], v[64:79]
	s_waitcnt lgkmcnt(5)
	v_mfma_f32_32x32x16_bf16 v[80:95], v[238:241], v[148:151], v[80:95]
	s_waitcnt lgkmcnt(4)
	v_mfma_f32_32x32x16_bf16 v[112:127], v[196:199], v[180:183], v[112:127]
	v_mfma_f32_32x32x16_bf16 v[96:111], v[238:241], v[180:183], v[96:111]
	s_waitcnt lgkmcnt(2)
	v_mfma_f32_32x32x16_bf16 v[64:79], v[200:203], v[160:163], v[64:79]
	s_waitcnt lgkmcnt(1)
	v_mfma_f32_32x32x16_bf16 v[80:95], v[242:245], v[160:163], v[80:95]
	s_waitcnt lgkmcnt(0)
	v_mfma_f32_32x32x16_bf16 v[112:127], v[200:203], v[184:187], v[112:127]
	v_mfma_f32_32x32x16_bf16 v[96:111], v[242:245], v[184:187], v[96:111]
	s_waitcnt vmcnt(2)
	s_barrier
	ds_read_b128 v[188:191], v232 offset:49152
	ds_read_b128 v[204:207], v232 offset:53248
	ds_read_b128 v[192:195], v233 offset:49152
	ds_read_b128 v[208:211], v233 offset:53248
	ds_read_b128 v[196:199], v237 offset:49152
	ds_read_b128 v[238:241], v237 offset:53248
	ds_read_b128 v[200:203], v252 offset:49152
	ds_read_b128 v[242:245], v252 offset:53248
	s_waitcnt lgkmcnt(7)
	v_mfma_f32_32x32x16_bf16 v[16:31], v[188:191], v[140:143], v[16:31]
	v_lshl_add_u64 v[246:247], v[132:133], 0, s[50:51]
	s_add_i32 m0, s4, 0x8000
	s_nop 0
	global_load_lds_dwordx4 v[246:247], off
	s_waitcnt lgkmcnt(6)
	v_mfma_f32_32x32x16_bf16 v[0:15], v[204:207], v[140:143], v[0:15]
	v_lshl_add_u64 v[248:249], v[134:135], 0, s[50:51]
	s_add_i32 m0, s4, 0x8400
	s_nop 0
	global_load_lds_dwordx4 v[248:249], off
	v_mfma_f32_32x32x16_bf16 v[48:63], v[188:191], v[164:167], v[48:63]
	v_lshl_add_u64 v[246:247], v[132:133], 0, s[50:51]
	v_lshl_add_u64 v[246:247], v[246:247], 0, s[54:55]
	s_add_i32 m0, s4, 0x8800
	s_nop 0
	global_load_lds_dwordx4 v[246:247], off
	v_mfma_f32_32x32x16_bf16 v[32:47], v[204:207], v[164:167], v[32:47]
	v_lshl_add_u64 v[248:249], v[134:135], 0, s[50:51]
	v_lshl_add_u64 v[248:249], v[248:249], 0, s[54:55]
	s_add_i32 m0, s4, 0x8c00
	s_nop 0
	global_load_lds_dwordx4 v[248:249], off
	s_waitcnt lgkmcnt(5)
	v_mfma_f32_32x32x16_bf16 v[16:31], v[192:195], v[144:147], v[16:31]
	v_lshl_add_u64 v[246:247], v[128:129], 0, s[50:51]
	v_lshl_add_u64 v[246:247], v[246:247], 0, s[52:53]
	s_add_i32 m0, s63, 0x6000
	s_nop 0
	global_load_lds_dwordx4 v[246:247], off
	s_waitcnt lgkmcnt(4)
	v_mfma_f32_32x32x16_bf16 v[0:15], v[208:211], v[144:147], v[0:15]
	v_lshl_add_u64 v[248:249], v[130:131], 0, s[50:51]
	v_lshl_add_u64 v[248:249], v[248:249], 0, s[52:53]
	s_add_i32 m0, s63, 0x6400
	s_nop 0
	global_load_lds_dwordx4 v[248:249], off
	s_add_u32 s48, s48, 0x80
	s_addc_u32 s49, s49, 0
	s_add_u32 s50, s50, 0x80
	s_addc_u32 s51, s51, 0
	v_mfma_f32_32x32x16_bf16 v[48:63], v[192:195], v[170:173], v[48:63]
	v_mfma_f32_32x32x16_bf16 v[32:47], v[208:211], v[170:173], v[32:47]
	s_waitcnt lgkmcnt(3)
	v_mfma_f32_32x32x16_bf16 v[16:31], v[196:199], v[148:151], v[16:31]
	s_waitcnt lgkmcnt(2)
	v_mfma_f32_32x32x16_bf16 v[0:15], v[238:241], v[148:151], v[0:15]
	v_mfma_f32_32x32x16_bf16 v[48:63], v[196:199], v[180:183], v[48:63]
	v_mfma_f32_32x32x16_bf16 v[32:47], v[238:241], v[180:183], v[32:47]
	s_waitcnt lgkmcnt(1)
	v_mfma_f32_32x32x16_bf16 v[16:31], v[200:203], v[160:163], v[16:31]
	s_waitcnt lgkmcnt(0)
	v_mfma_f32_32x32x16_bf16 v[0:15], v[242:245], v[160:163], v[0:15]
	v_mfma_f32_32x32x16_bf16 v[48:63], v[200:203], v[184:187], v[48:63]
	v_mfma_f32_32x32x16_bf16 v[32:47], v[242:245], v[184:187], v[32:47]
	s_waitcnt vmcnt(0)
	s_barrier
	ds_read_b128 v[140:143], v136 offset:16384
	ds_read_b128 v[188:191], v232 offset:32768
	ds_read_b128 v[204:207], v232 offset:36864
	ds_read_b128 v[164:167], v136 offset:20480
	ds_read_b128 v[144:147], v137 offset:16384
	ds_read_b128 v[192:195], v233 offset:32768
	ds_read_b128 v[208:211], v233 offset:36864
	ds_read_b128 v[170:173], v137 offset:20480
	s_waitcnt lgkmcnt(6)
	v_mfma_f32_32x32x16_bf16 v[64:79], v[188:191], v[140:143], v[64:79]
	v_lshl_add_u64 v[246:247], v[132:133], 0, s[48:49]
	v_lshl_add_u64 v[246:247], v[246:247], 0, s[52:53]
	s_add_i32 m0, s4, 0xc000
	s_nop 0
	global_load_lds_dwordx4 v[246:247], off
	s_waitcnt lgkmcnt(5)
	v_mfma_f32_32x32x16_bf16 v[80:95], v[204:207], v[140:143], v[80:95]
	v_lshl_add_u64 v[248:249], v[134:135], 0, s[48:49]
	v_lshl_add_u64 v[248:249], v[248:249], 0, s[52:53]
	s_add_i32 m0, s4, 0xc400
	s_nop 0
	global_load_lds_dwordx4 v[248:249], off
	s_waitcnt lgkmcnt(4)
	v_mfma_f32_32x32x16_bf16 v[112:127], v[188:191], v[164:167], v[112:127]
	v_lshl_add_u64 v[246:247], v[132:133], 0, s[48:49]
	v_lshl_add_u64 v[246:247], v[246:247], 0, s[52:53]
	v_lshl_add_u64 v[246:247], v[246:247], 0, s[54:55]
	s_add_i32 m0, s4, 0xc800
	s_nop 0
	global_load_lds_dwordx4 v[246:247], off
	v_mfma_f32_32x32x16_bf16 v[96:111], v[204:207], v[164:167], v[96:111]
	v_lshl_add_u64 v[248:249], v[134:135], 0, s[48:49]
	v_lshl_add_u64 v[248:249], v[248:249], 0, s[52:53]
	v_lshl_add_u64 v[248:249], v[248:249], 0, s[54:55]
	s_add_i32 m0, s4, 0xcc00
	s_nop 0
	global_load_lds_dwordx4 v[248:249], off
	ds_read_b128 v[148:151], v138 offset:16384
	ds_read_b128 v[196:199], v237 offset:32768
	ds_read_b128 v[238:241], v237 offset:36864
	ds_read_b128 v[180:183], v138 offset:20480
	s_waitcnt lgkmcnt(6)
	v_mfma_f32_32x32x16_bf16 v[64:79], v[192:195], v[144:147], v[64:79]
	v_lshl_add_u64 v[246:247], v[128:129], 0, s[50:51]
	s_add_i32 m0, s63, 0x0
	s_nop 0
	global_load_lds_dwordx4 v[246:247], off
	s_waitcnt lgkmcnt(5)
	v_mfma_f32_32x32x16_bf16 v[80:95], v[208:211], v[144:147], v[80:95]
	v_lshl_add_u64 v[248:249], v[130:131], 0, s[50:51]
	s_add_i32 m0, s63, 0x400
	s_nop 0
	global_load_lds_dwordx4 v[248:249], off
	s_waitcnt lgkmcnt(4)
	v_mfma_f32_32x32x16_bf16 v[112:127], v[192:195], v[170:173], v[112:127]
	v_mfma_f32_32x32x16_bf16 v[96:111], v[208:211], v[170:173], v[96:111]
	ds_read_b128 v[160:163], v139 offset:16384
	ds_read_b128 v[200:203], v252 offset:32768
	ds_read_b128 v[242:245], v252 offset:36864
	ds_read_b128 v[184:187], v139 offset:20480
	s_waitcnt lgkmcnt(6)
	v_mfma_f32_32x32x16_bf16 v[64:79], v[196:199], v[148:151], v[64:79]
	s_waitcnt lgkmcnt(5)
	v_mfma_f32_32x32x16_bf16 v[80:95], v[238:241], v[148:151], v[80:95]
	s_waitcnt lgkmcnt(4)
	v_mfma_f32_32x32x16_bf16 v[112:127], v[196:199], v[180:183], v[112:127]
	v_mfma_f32_32x32x16_bf16 v[96:111], v[238:241], v[180:183], v[96:111]
	s_waitcnt lgkmcnt(2)
	v_mfma_f32_32x32x16_bf16 v[64:79], v[200:203], v[160:163], v[64:79]
	s_waitcnt lgkmcnt(1)
	v_mfma_f32_32x32x16_bf16 v[80:95], v[242:245], v[160:163], v[80:95]
	s_waitcnt lgkmcnt(0)
	v_mfma_f32_32x32x16_bf16 v[112:127], v[200:203], v[184:187], v[112:127]
	v_mfma_f32_32x32x16_bf16 v[96:111], v[242:245], v[184:187], v[96:111]
	s_waitcnt vmcnt(2)
	s_barrier
	ds_read_b128 v[188:191], v232 offset:49152
	ds_read_b128 v[204:207], v232 offset:53248
	ds_read_b128 v[192:195], v233 offset:49152
	ds_read_b128 v[208:211], v233 offset:53248
	ds_read_b128 v[196:199], v237 offset:49152
	ds_read_b128 v[238:241], v237 offset:53248
	ds_read_b128 v[200:203], v252 offset:49152
	ds_read_b128 v[242:245], v252 offset:53248
	s_waitcnt lgkmcnt(7)
	v_mfma_f32_32x32x16_bf16 v[16:31], v[188:191], v[140:143], v[16:31]
	v_lshl_add_u64 v[246:247], v[132:133], 0, s[50:51]
	s_add_i32 m0, s4, 0x8000
	s_nop 0
	global_load_lds_dwordx4 v[246:247], off
	s_waitcnt lgkmcnt(6)
	v_mfma_f32_32x32x16_bf16 v[0:15], v[204:207], v[140:143], v[0:15]
	v_lshl_add_u64 v[248:249], v[134:135], 0, s[50:51]
	s_add_i32 m0, s4, 0x8400
	s_nop 0
	global_load_lds_dwordx4 v[248:249], off
	v_mfma_f32_32x32x16_bf16 v[48:63], v[188:191], v[164:167], v[48:63]
	v_lshl_add_u64 v[246:247], v[132:133], 0, s[50:51]
	v_lshl_add_u64 v[246:247], v[246:247], 0, s[54:55]
	s_add_i32 m0, s4, 0x8800
	s_nop 0
	global_load_lds_dwordx4 v[246:247], off
	v_mfma_f32_32x32x16_bf16 v[32:47], v[204:207], v[164:167], v[32:47]
	v_lshl_add_u64 v[248:249], v[134:135], 0, s[50:51]
	v_lshl_add_u64 v[248:249], v[248:249], 0, s[54:55]
	s_add_i32 m0, s4, 0x8c00
	s_nop 0
	global_load_lds_dwordx4 v[248:249], off
	s_waitcnt lgkmcnt(5)
	v_mfma_f32_32x32x16_bf16 v[16:31], v[192:195], v[144:147], v[16:31]
	v_lshl_add_u64 v[246:247], v[128:129], 0, s[50:51]
	v_lshl_add_u64 v[246:247], v[246:247], 0, s[52:53]
	s_add_i32 m0, s63, 0x2000
	s_nop 0
	global_load_lds_dwordx4 v[246:247], off
	s_waitcnt lgkmcnt(4)
	v_mfma_f32_32x32x16_bf16 v[0:15], v[208:211], v[144:147], v[0:15]
	v_lshl_add_u64 v[248:249], v[130:131], 0, s[50:51]
	v_lshl_add_u64 v[248:249], v[248:249], 0, s[52:53]
	s_add_i32 m0, s63, 0x2400
	s_nop 0
	global_load_lds_dwordx4 v[248:249], off
	s_add_u32 s48, s48, 0x80
	s_addc_u32 s49, s49, 0
	s_add_u32 s50, s50, 0x80
	s_addc_u32 s51, s51, 0
	v_mfma_f32_32x32x16_bf16 v[48:63], v[192:195], v[170:173], v[48:63]
	v_mfma_f32_32x32x16_bf16 v[32:47], v[208:211], v[170:173], v[32:47]
	s_waitcnt lgkmcnt(3)
	v_mfma_f32_32x32x16_bf16 v[16:31], v[196:199], v[148:151], v[16:31]
	s_waitcnt lgkmcnt(2)
	v_mfma_f32_32x32x16_bf16 v[0:15], v[238:241], v[148:151], v[0:15]
	v_mfma_f32_32x32x16_bf16 v[48:63], v[196:199], v[180:183], v[48:63]
	v_mfma_f32_32x32x16_bf16 v[32:47], v[238:241], v[180:183], v[32:47]
	s_waitcnt lgkmcnt(1)
	v_mfma_f32_32x32x16_bf16 v[16:31], v[200:203], v[160:163], v[16:31]
	s_waitcnt lgkmcnt(0)
	v_mfma_f32_32x32x16_bf16 v[0:15], v[242:245], v[160:163], v[0:15]
	v_mfma_f32_32x32x16_bf16 v[48:63], v[200:203], v[184:187], v[48:63]
	v_mfma_f32_32x32x16_bf16 v[32:47], v[242:245], v[184:187], v[32:47]
	s_add_i32 s5, s5, -1
	s_cmp_lg_u32 s5, 0
	s_cbranch_scc1 .Lk4_loop
	s_waitcnt vmcnt(0)
	s_barrier
	ds_read_b128 v[140:143], v136 offset:0
	ds_read_b128 v[188:191], v232 offset:32768
	ds_read_b128 v[204:207], v232 offset:36864
	ds_read_b128 v[164:167], v136 offset:4096
	ds_read_b128 v[144:147], v137 offset:0
	ds_read_b128 v[192:195], v233 offset:32768
	ds_read_b128 v[208:211], v233 offset:36864
	ds_read_b128 v[170:173], v137 offset:4096
	s_waitcnt lgkmcnt(6)
	v_mfma_f32_32x32x16_bf16 v[64:79], v[188:191], v[140:143], v[64:79]
	v_lshl_add_u64 v[246:247], v[132:133], 0, s[48:49]
	v_lshl_add_u64 v[246:247], v[246:247], 0, s[52:53]
	s_add_i32 m0, s4, 0xc000
	s_nop 0
	global_load_lds_dwordx4 v[246:247], off
	s_waitcnt lgkmcnt(5)
	v_mfma_f32_32x32x16_bf16 v[80:95], v[204:207], v[140:143], v[80:95]
	v_lshl_add_u64 v[248:249], v[134:135], 0, s[48:49]
	v_lshl_add_u64 v[248:249], v[248:249], 0, s[52:53]
	s_add_i32 m0, s4, 0xc400
	s_nop 0
	global_load_lds_dwordx4 v[248:249], off
	s_waitcnt lgkmcnt(4)
	v_mfma_f32_32x32x16_bf16 v[112:127], v[188:191], v[164:167], v[112:127]
	v_lshl_add_u64 v[246:247], v[132:133], 0, s[48:49]
	v_lshl_add_u64 v[246:247], v[246:247], 0, s[52:53]
	v_lshl_add_u64 v[246:247], v[246:247], 0, s[54:55]
	s_add_i32 m0, s4, 0xc800
	s_nop 0
	global_load_lds_dwordx4 v[246:247], off
	v_mfma_f32_32x32x16_bf16 v[96:111], v[204:207], v[164:167], v[96:111]
	v_lshl_add_u64 v[248:249], v[134:135], 0, s[48:49]
	v_lshl_add_u64 v[248:249], v[248:249], 0, s[52:53]
	v_lshl_add_u64 v[248:249], v[248:249], 0, s[54:55]
	s_add_i32 m0, s4, 0xcc00
	s_nop 0
	global_load_lds_dwordx4 v[248:249], off
	ds_read_b128 v[148:151], v138 offset:0
	ds_read_b128 v[196:199], v237 offset:32768
	ds_read_b128 v[238:241], v237 offset:36864
	ds_read_b128 v[180:183], v138 offset:4096
	s_waitcnt lgkmcnt(6)
	v_mfma_f32_32x32x16_bf16 v[64:79], v[192:195], v[144:147], v[64:79]
	v_lshl_add_u64 v[246:247], v[128:129], 0, s[50:51]
	s_add_i32 m0, s63, 0x4000
	s_nop 0
	global_load_lds_dwordx4 v[246:247], off
	s_waitcnt lgkmcnt(5)
	v_mfma_f32_32x32x16_bf16 v[80:95], v[208:211], v[144:147], v[80:95]
	v_lshl_add_u64 v[248:249], v[130:131], 0, s[50:51]
	s_add_i32 m0, s63, 0x4400
	s_nop 0
	global_load_lds_dwordx4 v[248:249], off
	s_waitcnt lgkmcnt(4)
	v_mfma_f32_32x32x16_bf16 v[112:127], v[192:195], v[170:173], v[112:127]
	v_mfma_f32_32x32x16_bf16 v[96:111], v[208:211], v[170:173], v[96:111]
	ds_read_b128 v[160:163], v139 offset:0
	ds_read_b128 v[200:203], v252 offset:32768
	ds_read_b128 v[242:245], v252 offset:36864
	ds_read_b128 v[184:187], v139 offset:4096
	s_waitcnt lgkmcnt(6)
	v_mfma_f32_32x32x16_bf16 v[64:79], v[196:199], v[148:151], v[64:79]
	s_waitcnt lgkmcnt(5)
	v_mfma_f32_32x32x16_bf16 v[80:95], v[238:241], v[148:151], v[80:95]
	s_waitcnt lgkmcnt(4)
	v_mfma_f32_32x32x16_bf16 v[112:127], v[196:199], v[180:183], v[112:127]
	v_mfma_f32_32x32x16_bf16 v[96:111], v[238:241], v[180:183], v[96:111]
	s_waitcnt lgkmcnt(2)
	v_mfma_f32_32x32x16_bf16 v[64:79], v[200:203], v[160:163], v[64:79]
	s_waitcnt lgkmcnt(1)
	v_mfma_f32_32x32x16_bf16 v[80:95], v[242:245], v[160:163], v[80:95]
	s_waitcnt lgkmcnt(0)
	v_mfma_f32_32x32x16_bf16 v[112:127], v[200:203], v[184:187], v[112:127]
	v_mfma_f32_32x32x16_bf16 v[96:111], v[242:245], v[184:187], v[96:111]
	s_waitcnt vmcnt(2)
	s_barrier
	ds_read_b128 v[188:191], v232 offset:49152
	ds_read_b128 v[204:207], v232 offset:53248
	ds_read_b128 v[192:195], v233 offset:49152
	ds_read_b128 v[208:211], v233 offset:53248
	ds_read_b128 v[196:199], v237 offset:49152
	ds_read_b128 v[238:241], v237 offset:53248
	ds_read_b128 v[200:203], v252 offset:49152
	ds_read_b128 v[242:245], v252 offset:53248
	s_waitcnt lgkmcnt(7)
	v_mfma_f32_32x32x16_bf16 v[16:31], v[188:191], v[140:143], v[16:31]
	v_lshl_add_u64 v[246:247], v[132:133], 0, s[50:51]
	s_add_i32 m0, s4, 0x8000
	s_nop 0
	global_load_lds_dwordx4 v[246:247], off
	s_waitcnt lgkmcnt(6)
	v_mfma_f32_32x32x16_bf16 v[0:15], v[204:207], v[140:143], v[0:15]
	v_lshl_add_u64 v[248:249], v[134:135], 0, s[50:51]
	s_add_i32 m0, s4, 0x8400
	s_nop 0
	global_load_lds_dwordx4 v[248:249], off
	v_mfma_f32_32x32x16_bf16 v[48:63], v[188:191], v[164:167], v[48:63]
	v_lshl_add_u64 v[246:247], v[132:133], 0, s[50:51]
	v_lshl_add_u64 v[246:247], v[246:247], 0, s[54:55]
	s_add_i32 m0, s4, 0x8800
	s_nop 0
	global_load_lds_dwordx4 v[246:247], off
	v_mfma_f32_32x32x16_bf16 v[32:47], v[204:207], v[164:167], v[32:47]
	v_lshl_add_u64 v[248:249], v[134:135], 0, s[50:51]
	v_lshl_add_u64 v[248:249], v[248:249], 0, s[54:55]
	s_add_i32 m0, s4, 0x8c00
	s_nop 0
	global_load_lds_dwordx4 v[248:249], off
	s_waitcnt lgkmcnt(5)
	v_mfma_f32_32x32x16_bf16 v[16:31], v[192:195], v[144:147], v[16:31]
	v_lshl_add_u64 v[246:247], v[128:129], 0, s[50:51]
	v_lshl_add_u64 v[246:247], v[246:247], 0, s[52:53]
	s_add_i32 m0, s63, 0x6000
	s_nop 0
	global_load_lds_dwordx4 v[246:247], off
	s_waitcnt lgkmcnt(4)
	v_mfma_f32_32x32x16_bf16 v[0:15], v[208:211], v[144:147], v[0:15]
	v_lshl_add_u64 v[248:249], v[130:131], 0, s[50:51]
	v_lshl_add_u64 v[248:249], v[248:249], 0, s[52:53]
	s_add_i32 m0, s63, 0x6400
	s_nop 0
	global_load_lds_dwordx4 v[248:249], off
	s_add_u32 s48, s48, 0x80
	s_addc_u32 s49, s49, 0
	s_add_u32 s50, s50, 0x80
	s_addc_u32 s51, s51, 0
	v_mfma_f32_32x32x16_bf16 v[48:63], v[192:195], v[170:173], v[48:63]
	v_mfma_f32_32x32x16_bf16 v[32:47], v[208:211], v[170:173], v[32:47]
	s_waitcnt lgkmcnt(3)
	v_mfma_f32_32x32x16_bf16 v[16:31], v[196:199], v[148:151], v[16:31]
	s_waitcnt lgkmcnt(2)
	v_mfma_f32_32x32x16_bf16 v[0:15], v[238:241], v[148:151], v[0:15]
	v_mfma_f32_32x32x16_bf16 v[48:63], v[196:199], v[180:183], v[48:63]
	v_mfma_f32_32x32x16_bf16 v[32:47], v[238:241], v[180:183], v[32:47]
	s_waitcnt lgkmcnt(1)
	v_mfma_f32_32x32x16_bf16 v[16:31], v[200:203], v[160:163], v[16:31]
	s_waitcnt lgkmcnt(0)
	v_mfma_f32_32x32x16_bf16 v[0:15], v[242:245], v[160:163], v[0:15]
	v_mfma_f32_32x32x16_bf16 v[48:63], v[200:203], v[184:187], v[48:63]
	v_mfma_f32_32x32x16_bf16 v[32:47], v[242:245], v[184:187], v[32:47]
	s_waitcnt vmcnt(0)
	s_barrier
	ds_read_b128 v[140:143], v136 offset:16384
	ds_read_b128 v[188:191], v232 offset:32768
	ds_read_b128 v[204:207], v232 offset:36864
	ds_read_b128 v[164:167], v136 offset:20480
	ds_read_b128 v[144:147], v137 offset:16384
	ds_read_b128 v[192:195], v233 offset:32768
	ds_read_b128 v[208:211], v233 offset:36864
	ds_read_b128 v[170:173], v137 offset:20480
	s_waitcnt lgkmcnt(6)
	v_mfma_f32_32x32x16_bf16 v[64:79], v[188:191], v[140:143], v[64:79]
	v_lshl_add_u64 v[246:247], v[132:133], 0, s[48:49]
	v_lshl_add_u64 v[246:247], v[246:247], 0, s[52:53]
	s_add_i32 m0, s4, 0xc000
	s_nop 0
	global_load_lds_dwordx4 v[246:247], off
	s_waitcnt lgkmcnt(5)
	v_mfma_f32_32x32x16_bf16 v[80:95], v[204:207], v[140:143], v[80:95]
	v_lshl_add_u64 v[248:249], v[134:135], 0, s[48:49]
	v_lshl_add_u64 v[248:249], v[248:249], 0, s[52:53]
	s_add_i32 m0, s4, 0xc400
	s_nop 0
	global_load_lds_dwordx4 v[248:249], off
	s_waitcnt lgkmcnt(4)
	v_mfma_f32_32x32x16_bf16 v[112:127], v[188:191], v[164:167], v[112:127]
	v_lshl_add_u64 v[246:247], v[132:133], 0, s[48:49]
	v_lshl_add_u64 v[246:247], v[246:247], 0, s[52:53]
	v_lshl_add_u64 v[246:247], v[246:247], 0, s[54:55]
	s_add_i32 m0, s4, 0xc800
	s_nop 0
	global_load_lds_dwordx4 v[246:247], off
	v_mfma_f32_32x32x16_bf16 v[96:111], v[204:207], v[164:167], v[96:111]
	v_lshl_add_u64 v[248:249], v[134:135], 0, s[48:49]
	v_lshl_add_u64 v[248:249], v[248:249], 0, s[52:53]
	v_lshl_add_u64 v[248:249], v[248:249], 0, s[54:55]
	s_add_i32 m0, s4, 0xcc00
	s_nop 0
	global_load_lds_dwordx4 v[248:249], off
	ds_read_b128 v[148:151], v138 offset:16384
	ds_read_b128 v[196:199], v237 offset:32768
	ds_read_b128 v[238:241], v237 offset:36864
	ds_read_b128 v[180:183], v138 offset:20480
	s_waitcnt lgkmcnt(6)
	v_mfma_f32_32x32x16_bf16 v[64:79], v[192:195], v[144:147], v[64:79]
	s_waitcnt lgkmcnt(5)
	v_mfma_f32_32x32x16_bf16 v[80:95], v[208:211], v[144:147], v[80:95]
	s_waitcnt lgkmcnt(4)
	v_mfma_f32_32x32x16_bf16 v[112:127], v[192:195], v[170:173], v[112:127]
	v_mfma_f32_32x32x16_bf16 v[96:111], v[208:211], v[170:173], v[96:111]
	ds_read_b128 v[160:163], v139 offset:16384
	ds_read_b128 v[200:203], v252 offset:32768
	ds_read_b128 v[242:245], v252 offset:36864
	ds_read_b128 v[184:187], v139 offset:20480
	s_waitcnt lgkmcnt(6)
	v_mfma_f32_32x32x16_bf16 v[64:79], v[196:199], v[148:151], v[64:79]
	s_waitcnt lgkmcnt(5)
	v_mfma_f32_32x32x16_bf16 v[80:95], v[238:241], v[148:151], v[80:95]
	s_waitcnt lgkmcnt(4)
	v_mfma_f32_32x32x16_bf16 v[112:127], v[196:199], v[180:183], v[112:127]
	v_mfma_f32_32x32x16_bf16 v[96:111], v[238:241], v[180:183], v[96:111]
	s_waitcnt lgkmcnt(2)
	v_mfma_f32_32x32x16_bf16 v[64:79], v[200:203], v[160:163], v[64:79]
	s_waitcnt lgkmcnt(1)
	v_mfma_f32_32x32x16_bf16 v[80:95], v[242:245], v[160:163], v[80:95]
	s_waitcnt lgkmcnt(0)
	v_mfma_f32_32x32x16_bf16 v[112:127], v[200:203], v[184:187], v[112:127]
	v_mfma_f32_32x32x16_bf16 v[96:111], v[242:245], v[184:187], v[96:111]
	s_waitcnt vmcnt(0)
	s_barrier
	ds_read_b128 v[188:191], v232 offset:49152
	ds_read_b128 v[204:207], v232 offset:53248
	ds_read_b128 v[192:195], v233 offset:49152
	ds_read_b128 v[208:211], v233 offset:53248
	ds_read_b128 v[196:199], v237 offset:49152
	ds_read_b128 v[238:241], v237 offset:53248
	ds_read_b128 v[200:203], v252 offset:49152
	ds_read_b128 v[242:245], v252 offset:53248
	s_waitcnt lgkmcnt(7)
	v_mfma_f32_32x32x16_bf16 v[16:31], v[188:191], v[140:143], v[16:31]
	s_waitcnt lgkmcnt(6)
	v_mfma_f32_32x32x16_bf16 v[0:15], v[204:207], v[140:143], v[0:15]
	v_mfma_f32_32x32x16_bf16 v[48:63], v[188:191], v[164:167], v[48:63]
	v_mfma_f32_32x32x16_bf16 v[32:47], v[204:207], v[164:167], v[32:47]
	s_waitcnt lgkmcnt(5)
	v_mfma_f32_32x32x16_bf16 v[16:31], v[192:195], v[144:147], v[16:31]
	s_waitcnt lgkmcnt(4)
	v_mfma_f32_32x32x16_bf16 v[0:15], v[208:211], v[144:147], v[0:15]
	v_mfma_f32_32x32x16_bf16 v[48:63], v[192:195], v[170:173], v[48:63]
	v_mfma_f32_32x32x16_bf16 v[32:47], v[208:211], v[170:173], v[32:47]
	s_waitcnt lgkmcnt(3)
	v_mfma_f32_32x32x16_bf16 v[16:31], v[196:199], v[148:151], v[16:31]
	s_waitcnt lgkmcnt(2)
	v_mfma_f32_32x32x16_bf16 v[0:15], v[238:241], v[148:151], v[0:15]
	v_mfma_f32_32x32x16_bf16 v[48:63], v[196:199], v[180:183], v[48:63]
	v_mfma_f32_32x32x16_bf16 v[32:47], v[238:241], v[180:183], v[32:47]
	s_waitcnt lgkmcnt(1)
	v_mfma_f32_32x32x16_bf16 v[16:31], v[200:203], v[160:163], v[16:31]
	s_waitcnt lgkmcnt(0)
	v_mfma_f32_32x32x16_bf16 v[0:15], v[242:245], v[160:163], v[0:15]
	v_mfma_f32_32x32x16_bf16 v[48:63], v[200:203], v[184:187], v[48:63]
	v_mfma_f32_32x32x16_bf16 v[32:47], v[242:245], v[184:187], v[32:47]

.Lk3_loop:
	s_waitcnt vmcnt(0)
	s_barrier
	ds_read_b128 v[140:143], v136 offset:0
	ds_read_b128 v[188:191], v232 offset:32768
	ds_read_b128 v[204:207], v232 offset:36864
	ds_read_b128 v[164:167], v136 offset:4096
	ds_read_b128 v[144:147], v137 offset:0
	ds_read_b128 v[192:195], v233 offset:32768
	ds_read_b128 v[208:211], v233 offset:36864
	ds_read_b128 v[170:173], v137 offset:4096
	s_waitcnt lgkmcnt(6)
	v_mfma_f32_32x32x16_bf16 v[96:111], v[188:191], v[140:143], v[96:111]
	v_lshl_add_u64 v[246:247], v[132:133], 0, s[48:49]
	v_lshl_add_u64 v[246:247], v[246:247], 0, s[52:53]
	s_add_i32 m0, s10, 0xc000
	s_nop 0
	global_load_lds_dwordx4 v[246:247], off
	s_waitcnt lgkmcnt(5)
	v_mfma_f32_32x32x16_bf16 v[112:127], v[204:207], v[140:143], v[112:127]
	v_lshl_add_u64 v[248:249], v[134:135], 0, s[48:49]
	v_lshl_add_u64 v[248:249], v[248:249], 0, s[52:53]
	s_add_i32 m0, s10, 0xc400
	s_nop 0
	global_load_lds_dwordx4 v[248:249], off
	s_waitcnt lgkmcnt(4)
	v_mfma_f32_32x32x16_bf16 v[64:79], v[188:191], v[164:167], v[64:79]
	v_lshl_add_u64 v[246:247], v[132:133], 0, s[48:49]
	v_lshl_add_u64 v[246:247], v[246:247], 0, s[52:53]
	v_lshl_add_u64 v[246:247], v[246:247], 0, s[54:55]
	s_add_i32 m0, s10, 0xc800
	s_nop 0
	global_load_lds_dwordx4 v[246:247], off
	v_mfma_f32_32x32x16_bf16 v[80:95], v[204:207], v[164:167], v[80:95]
	v_lshl_add_u64 v[248:249], v[134:135], 0, s[48:49]
	v_lshl_add_u64 v[248:249], v[248:249], 0, s[52:53]
	v_lshl_add_u64 v[248:249], v[248:249], 0, s[54:55]
	s_add_i32 m0, s10, 0xcc00
	s_nop 0
	global_load_lds_dwordx4 v[248:249], off
	ds_read_b128 v[148:151], v138 offset:0
	ds_read_b128 v[196:199], v237 offset:32768
	ds_read_b128 v[238:241], v237 offset:36864
	ds_read_b128 v[180:183], v138 offset:4096
	s_waitcnt lgkmcnt(6)
	v_mfma_f32_32x32x16_bf16 v[96:111], v[192:195], v[144:147], v[96:111]
	v_lshl_add_u64 v[246:247], v[128:129], 0, s[50:51]
	s_add_i32 m0, s63, 0x4000
	s_nop 0
	global_load_lds_dwordx4 v[246:247], off
	s_waitcnt lgkmcnt(5)
	v_mfma_f32_32x32x16_bf16 v[112:127], v[208:211], v[144:147], v[112:127]
	v_lshl_add_u64 v[248:249], v[130:131], 0, s[50:51]
	s_add_i32 m0, s63, 0x4400
	s_nop 0
	global_load_lds_dwordx4 v[248:249], off
	s_waitcnt lgkmcnt(4)
	v_mfma_f32_32x32x16_bf16 v[64:79], v[192:195], v[170:173], v[64:79]
	v_mfma_f32_32x32x16_bf16 v[80:95], v[208:211], v[170:173], v[80:95]
	ds_read_b128 v[160:163], v139 offset:0
	ds_read_b128 v[200:203], v252 offset:32768
	ds_read_b128 v[242:245], v252 offset:36864
	ds_read_b128 v[184:187], v139 offset:4096
	s_waitcnt lgkmcnt(6)
	v_mfma_f32_32x32x16_bf16 v[96:111], v[196:199], v[148:151], v[96:111]
	s_waitcnt lgkmcnt(5)
	v_mfma_f32_32x32x16_bf16 v[112:127], v[238:241], v[148:151], v[112:127]
	s_waitcnt lgkmcnt(4)
	v_mfma_f32_32x32x16_bf16 v[64:79], v[196:199], v[180:183], v[64:79]
	v_mfma_f32_32x32x16_bf16 v[80:95], v[238:241], v[180:183], v[80:95]
	s_waitcnt lgkmcnt(2)
	v_mfma_f32_32x32x16_bf16 v[96:111], v[200:203], v[160:163], v[96:111]
	s_waitcnt lgkmcnt(1)
	v_mfma_f32_32x32x16_bf16 v[112:127], v[242:245], v[160:163], v[112:127]
	s_waitcnt lgkmcnt(0)
	v_mfma_f32_32x32x16_bf16 v[64:79], v[200:203], v[184:187], v[64:79]
	v_mfma_f32_32x32x16_bf16 v[80:95], v[242:245], v[184:187], v[80:95]
	s_waitcnt vmcnt(2)
	s_barrier
	ds_read_b128 v[188:191], v232 offset:49152
	ds_read_b128 v[204:207], v232 offset:53248
	ds_read_b128 v[192:195], v233 offset:49152
	ds_read_b128 v[208:211], v233 offset:53248
	ds_read_b128 v[196:199], v237 offset:49152
	ds_read_b128 v[238:241], v237 offset:53248
	ds_read_b128 v[200:203], v252 offset:49152
	ds_read_b128 v[242:245], v252 offset:53248
	s_waitcnt lgkmcnt(7)
	v_mfma_f32_32x32x16_bf16 v[32:47], v[188:191], v[140:143], v[32:47]
	v_lshl_add_u64 v[246:247], v[132:133], 0, s[50:51]
	s_add_i32 m0, s10, 0x8000
	s_nop 0
	global_load_lds_dwordx4 v[246:247], off
	s_waitcnt lgkmcnt(6)
	v_mfma_f32_32x32x16_bf16 v[48:63], v[204:207], v[140:143], v[48:63]
	v_lshl_add_u64 v[248:249], v[134:135], 0, s[50:51]
	s_add_i32 m0, s10, 0x8400
	s_nop 0
	global_load_lds_dwordx4 v[248:249], off
	v_mfma_f32_32x32x16_bf16 v[0:15], v[188:191], v[164:167], v[0:15]
	v_lshl_add_u64 v[246:247], v[132:133], 0, s[50:51]
	v_lshl_add_u64 v[246:247], v[246:247], 0, s[54:55]
	s_add_i32 m0, s10, 0x8800
	s_nop 0
	global_load_lds_dwordx4 v[246:247], off
	v_mfma_f32_32x32x16_bf16 v[16:31], v[204:207], v[164:167], v[16:31]
	v_lshl_add_u64 v[248:249], v[134:135], 0, s[50:51]
	v_lshl_add_u64 v[248:249], v[248:249], 0, s[54:55]
	s_add_i32 m0, s10, 0x8c00
	s_nop 0
	global_load_lds_dwordx4 v[248:249], off
	s_waitcnt lgkmcnt(5)
	v_mfma_f32_32x32x16_bf16 v[32:47], v[192:195], v[144:147], v[32:47]
	v_lshl_add_u64 v[246:247], v[128:129], 0, s[50:51]
	v_lshl_add_u64 v[246:247], v[246:247], 0, s[52:53]
	s_add_i32 m0, s63, 0x6000
	s_nop 0
	global_load_lds_dwordx4 v[246:247], off
	s_waitcnt lgkmcnt(4)
	v_mfma_f32_32x32x16_bf16 v[48:63], v[208:211], v[144:147], v[48:63]
	v_lshl_add_u64 v[248:249], v[130:131], 0, s[50:51]
	v_lshl_add_u64 v[248:249], v[248:249], 0, s[52:53]
	s_add_i32 m0, s63, 0x6400
	s_nop 0
	global_load_lds_dwordx4 v[248:249], off
	s_add_u32 s48, s48, 0x80
	s_addc_u32 s49, s49, 0
	s_add_u32 s50, s50, 0x80
	s_addc_u32 s51, s51, 0
	v_mfma_f32_32x32x16_bf16 v[0:15], v[192:195], v[170:173], v[0:15]
	v_mfma_f32_32x32x16_bf16 v[16:31], v[208:211], v[170:173], v[16:31]
	s_waitcnt lgkmcnt(3)
	v_mfma_f32_32x32x16_bf16 v[32:47], v[196:199], v[148:151], v[32:47]
	s_waitcnt lgkmcnt(2)
	v_mfma_f32_32x32x16_bf16 v[48:63], v[238:241], v[148:151], v[48:63]
	v_mfma_f32_32x32x16_bf16 v[0:15], v[196:199], v[180:183], v[0:15]
	v_mfma_f32_32x32x16_bf16 v[16:31], v[238:241], v[180:183], v[16:31]
	s_waitcnt lgkmcnt(1)
	v_mfma_f32_32x32x16_bf16 v[32:47], v[200:203], v[160:163], v[32:47]
	s_waitcnt lgkmcnt(0)
	v_mfma_f32_32x32x16_bf16 v[48:63], v[242:245], v[160:163], v[48:63]
	v_mfma_f32_32x32x16_bf16 v[0:15], v[200:203], v[184:187], v[0:15]
	v_mfma_f32_32x32x16_bf16 v[16:31], v[242:245], v[184:187], v[16:31]
	s_waitcnt vmcnt(0)
	s_barrier
	ds_read_b128 v[140:143], v136 offset:16384
	ds_read_b128 v[188:191], v232 offset:32768
	ds_read_b128 v[204:207], v232 offset:36864
	ds_read_b128 v[164:167], v136 offset:20480
	ds_read_b128 v[144:147], v137 offset:16384
	ds_read_b128 v[192:195], v233 offset:32768
	ds_read_b128 v[208:211], v233 offset:36864
	ds_read_b128 v[170:173], v137 offset:20480
	s_waitcnt lgkmcnt(6)
	v_mfma_f32_32x32x16_bf16 v[96:111], v[188:191], v[140:143], v[96:111]
	v_lshl_add_u64 v[246:247], v[132:133], 0, s[48:49]
	v_lshl_add_u64 v[246:247], v[246:247], 0, s[52:53]
	s_add_i32 m0, s10, 0xc000
	s_nop 0
	global_load_lds_dwordx4 v[246:247], off
	s_waitcnt lgkmcnt(5)
	v_mfma_f32_32x32x16_bf16 v[112:127], v[204:207], v[140:143], v[112:127]
	v_lshl_add_u64 v[248:249], v[134:135], 0, s[48:49]
	v_lshl_add_u64 v[248:249], v[248:249], 0, s[52:53]
	s_add_i32 m0, s10, 0xc400
	s_nop 0
	global_load_lds_dwordx4 v[248:249], off
	s_waitcnt lgkmcnt(4)
	v_mfma_f32_32x32x16_bf16 v[64:79], v[188:191], v[164:167], v[64:79]
	v_lshl_add_u64 v[246:247], v[132:133], 0, s[48:49]
	v_lshl_add_u64 v[246:247], v[246:247], 0, s[52:53]
	v_lshl_add_u64 v[246:247], v[246:247], 0, s[54:55]
	s_add_i32 m0, s10, 0xc800
	s_nop 0
	global_load_lds_dwordx4 v[246:247], off
	v_mfma_f32_32x32x16_bf16 v[80:95], v[204:207], v[164:167], v[80:95]
	v_lshl_add_u64 v[248:249], v[134:135], 0, s[48:49]
	v_lshl_add_u64 v[248:249], v[248:249], 0, s[52:53]
	v_lshl_add_u64 v[248:249], v[248:249], 0, s[54:55]
	s_add_i32 m0, s10, 0xcc00
	s_nop 0
	global_load_lds_dwordx4 v[248:249], off
	ds_read_b128 v[148:151], v138 offset:16384
	ds_read_b128 v[196:199], v237 offset:32768
	ds_read_b128 v[238:241], v237 offset:36864
	ds_read_b128 v[180:183], v138 offset:20480
	s_waitcnt lgkmcnt(6)
	v_mfma_f32_32x32x16_bf16 v[96:111], v[192:195], v[144:147], v[96:111]
	v_lshl_add_u64 v[246:247], v[128:129], 0, s[50:51]
	s_add_i32 m0, s63, 0x0
	s_nop 0
	global_load_lds_dwordx4 v[246:247], off
	s_waitcnt lgkmcnt(5)
	v_mfma_f32_32x32x16_bf16 v[112:127], v[208:211], v[144:147], v[112:127]
	v_lshl_add_u64 v[248:249], v[130:131], 0, s[50:51]
	s_add_i32 m0, s63, 0x400
	s_nop 0
	global_load_lds_dwordx4 v[248:249], off
	s_waitcnt lgkmcnt(4)
	v_mfma_f32_32x32x16_bf16 v[64:79], v[192:195], v[170:173], v[64:79]
	v_mfma_f32_32x32x16_bf16 v[80:95], v[208:211], v[170:173], v[80:95]
	ds_read_b128 v[160:163], v139 offset:16384
	ds_read_b128 v[200:203], v252 offset:32768
	ds_read_b128 v[242:245], v252 offset:36864
	ds_read_b128 v[184:187], v139 offset:20480
	s_waitcnt lgkmcnt(6)
	v_mfma_f32_32x32x16_bf16 v[96:111], v[196:199], v[148:151], v[96:111]
	s_waitcnt lgkmcnt(5)
	v_mfma_f32_32x32x16_bf16 v[112:127], v[238:241], v[148:151], v[112:127]
	s_waitcnt lgkmcnt(4)
	v_mfma_f32_32x32x16_bf16 v[64:79], v[196:199], v[180:183], v[64:79]
	v_mfma_f32_32x32x16_bf16 v[80:95], v[238:241], v[180:183], v[80:95]
	s_waitcnt lgkmcnt(2)
	v_mfma_f32_32x32x16_bf16 v[96:111], v[200:203], v[160:163], v[96:111]
	s_waitcnt lgkmcnt(1)
	v_mfma_f32_32x32x16_bf16 v[112:127], v[242:245], v[160:163], v[112:127]
	s_waitcnt lgkmcnt(0)
	v_mfma_f32_32x32x16_bf16 v[64:79], v[200:203], v[184:187], v[64:79]
	v_mfma_f32_32x32x16_bf16 v[80:95], v[242:245], v[184:187], v[80:95]
	s_waitcnt vmcnt(2)
	s_barrier
	ds_read_b128 v[188:191], v232 offset:49152
	ds_read_b128 v[204:207], v232 offset:53248
	ds_read_b128 v[192:195], v233 offset:49152
	ds_read_b128 v[208:211], v233 offset:53248
	ds_read_b128 v[196:199], v237 offset:49152
	ds_read_b128 v[238:241], v237 offset:53248
	ds_read_b128 v[200:203], v252 offset:49152
	ds_read_b128 v[242:245], v252 offset:53248
	s_waitcnt lgkmcnt(7)
	v_mfma_f32_32x32x16_bf16 v[32:47], v[188:191], v[140:143], v[32:47]
	v_lshl_add_u64 v[246:247], v[132:133], 0, s[50:51]
	s_add_i32 m0, s10, 0x8000
	s_nop 0
	global_load_lds_dwordx4 v[246:247], off
	s_waitcnt lgkmcnt(6)
	v_mfma_f32_32x32x16_bf16 v[48:63], v[204:207], v[140:143], v[48:63]
	v_lshl_add_u64 v[248:249], v[134:135], 0, s[50:51]
	s_add_i32 m0, s10, 0x8400
	s_nop 0
	global_load_lds_dwordx4 v[248:249], off
	v_mfma_f32_32x32x16_bf16 v[0:15], v[188:191], v[164:167], v[0:15]
	v_lshl_add_u64 v[246:247], v[132:133], 0, s[50:51]
	v_lshl_add_u64 v[246:247], v[246:247], 0, s[54:55]
	s_add_i32 m0, s10, 0x8800
	s_nop 0
	global_load_lds_dwordx4 v[246:247], off
	v_mfma_f32_32x32x16_bf16 v[16:31], v[204:207], v[164:167], v[16:31]
	v_lshl_add_u64 v[248:249], v[134:135], 0, s[50:51]
	v_lshl_add_u64 v[248:249], v[248:249], 0, s[54:55]
	s_add_i32 m0, s10, 0x8c00
	s_nop 0
	global_load_lds_dwordx4 v[248:249], off
	s_waitcnt lgkmcnt(5)
	v_mfma_f32_32x32x16_bf16 v[32:47], v[192:195], v[144:147], v[32:47]
	v_lshl_add_u64 v[246:247], v[128:129], 0, s[50:51]
	v_lshl_add_u64 v[246:247], v[246:247], 0, s[52:53]
	s_add_i32 m0, s63, 0x2000
	s_nop 0
	global_load_lds_dwordx4 v[246:247], off
	s_waitcnt lgkmcnt(4)
	v_mfma_f32_32x32x16_bf16 v[48:63], v[208:211], v[144:147], v[48:63]
	v_lshl_add_u64 v[248:249], v[130:131], 0, s[50:51]
	v_lshl_add_u64 v[248:249], v[248:249], 0, s[52:53]
	s_add_i32 m0, s63, 0x2400
	s_nop 0
	global_load_lds_dwordx4 v[248:249], off
	s_add_u32 s48, s48, 0x80
	s_addc_u32 s49, s49, 0
	s_add_u32 s50, s50, 0x80
	s_addc_u32 s51, s51, 0
	v_mfma_f32_32x32x16_bf16 v[0:15], v[192:195], v[170:173], v[0:15]
	v_mfma_f32_32x32x16_bf16 v[16:31], v[208:211], v[170:173], v[16:31]
	s_waitcnt lgkmcnt(3)
	v_mfma_f32_32x32x16_bf16 v[32:47], v[196:199], v[148:151], v[32:47]
	s_waitcnt lgkmcnt(2)
	v_mfma_f32_32x32x16_bf16 v[48:63], v[238:241], v[148:151], v[48:63]
	v_mfma_f32_32x32x16_bf16 v[0:15], v[196:199], v[180:183], v[0:15]
	v_mfma_f32_32x32x16_bf16 v[16:31], v[238:241], v[180:183], v[16:31]
	s_waitcnt lgkmcnt(1)
	v_mfma_f32_32x32x16_bf16 v[32:47], v[200:203], v[160:163], v[32:47]
	s_waitcnt lgkmcnt(0)
	v_mfma_f32_32x32x16_bf16 v[48:63], v[242:245], v[160:163], v[48:63]
	v_mfma_f32_32x32x16_bf16 v[0:15], v[200:203], v[184:187], v[0:15]
	v_mfma_f32_32x32x16_bf16 v[16:31], v[242:245], v[184:187], v[16:31]
	s_add_i32 s11, s11, -1
	s_cmp_lg_u32 s11, 0
	s_cbranch_scc1 .Lk3_loop
	s_waitcnt vmcnt(0)
	s_barrier
	ds_read_b128 v[140:143], v136 offset:0
	ds_read_b128 v[188:191], v232 offset:32768
	ds_read_b128 v[204:207], v232 offset:36864
	ds_read_b128 v[164:167], v136 offset:4096
	ds_read_b128 v[144:147], v137 offset:0
	ds_read_b128 v[192:195], v233 offset:32768
	ds_read_b128 v[208:211], v233 offset:36864
	ds_read_b128 v[170:173], v137 offset:4096
	s_waitcnt lgkmcnt(6)
	v_mfma_f32_32x32x16_bf16 v[96:111], v[188:191], v[140:143], v[96:111]
	v_lshl_add_u64 v[246:247], v[132:133], 0, s[48:49]
	v_lshl_add_u64 v[246:247], v[246:247], 0, s[52:53]
	s_add_i32 m0, s10, 0xc000
	s_nop 0
	global_load_lds_dwordx4 v[246:247], off
	s_waitcnt lgkmcnt(5)
	v_mfma_f32_32x32x16_bf16 v[112:127], v[204:207], v[140:143], v[112:127]
	v_lshl_add_u64 v[248:249], v[134:135], 0, s[48:49]
	v_lshl_add_u64 v[248:249], v[248:249], 0, s[52:53]
	s_add_i32 m0, s10, 0xc400
	s_nop 0
	global_load_lds_dwordx4 v[248:249], off
	s_waitcnt lgkmcnt(4)
	v_mfma_f32_32x32x16_bf16 v[64:79], v[188:191], v[164:167], v[64:79]
	v_lshl_add_u64 v[246:247], v[132:133], 0, s[48:49]
	v_lshl_add_u64 v[246:247], v[246:247], 0, s[52:53]
	v_lshl_add_u64 v[246:247], v[246:247], 0, s[54:55]
	s_add_i32 m0, s10, 0xc800
	s_nop 0
	global_load_lds_dwordx4 v[246:247], off
	v_mfma_f32_32x32x16_bf16 v[80:95], v[204:207], v[164:167], v[80:95]
	v_lshl_add_u64 v[248:249], v[134:135], 0, s[48:49]
	v_lshl_add_u64 v[248:249], v[248:249], 0, s[52:53]
	v_lshl_add_u64 v[248:249], v[248:249], 0, s[54:55]
	s_add_i32 m0, s10, 0xcc00
	s_nop 0
	global_load_lds_dwordx4 v[248:249], off
	ds_read_b128 v[148:151], v138 offset:0
	ds_read_b128 v[196:199], v237 offset:32768
	ds_read_b128 v[238:241], v237 offset:36864
	ds_read_b128 v[180:183], v138 offset:4096
	s_waitcnt lgkmcnt(6)
	v_mfma_f32_32x32x16_bf16 v[96:111], v[192:195], v[144:147], v[96:111]
	v_lshl_add_u64 v[246:247], v[128:129], 0, s[50:51]
	s_add_i32 m0, s63, 0x4000
	s_nop 0
	global_load_lds_dwordx4 v[246:247], off
	s_waitcnt lgkmcnt(5)
	v_mfma_f32_32x32x16_bf16 v[112:127], v[208:211], v[144:147], v[112:127]
	v_lshl_add_u64 v[248:249], v[130:131], 0, s[50:51]
	s_add_i32 m0, s63, 0x4400
	s_nop 0
	global_load_lds_dwordx4 v[248:249], off
	s_waitcnt lgkmcnt(4)
	v_mfma_f32_32x32x16_bf16 v[64:79], v[192:195], v[170:173], v[64:79]
	v_mfma_f32_32x32x16_bf16 v[80:95], v[208:211], v[170:173], v[80:95]
	ds_read_b128 v[160:163], v139 offset:0
	ds_read_b128 v[200:203], v252 offset:32768
	ds_read_b128 v[242:245], v252 offset:36864
	ds_read_b128 v[184:187], v139 offset:4096
	s_waitcnt lgkmcnt(6)
	v_mfma_f32_32x32x16_bf16 v[96:111], v[196:199], v[148:151], v[96:111]
	s_waitcnt lgkmcnt(5)
	v_mfma_f32_32x32x16_bf16 v[112:127], v[238:241], v[148:151], v[112:127]
	s_waitcnt lgkmcnt(4)
	v_mfma_f32_32x32x16_bf16 v[64:79], v[196:199], v[180:183], v[64:79]
	v_mfma_f32_32x32x16_bf16 v[80:95], v[238:241], v[180:183], v[80:95]
	s_waitcnt lgkmcnt(2)
	v_mfma_f32_32x32x16_bf16 v[96:111], v[200:203], v[160:163], v[96:111]
	s_waitcnt lgkmcnt(1)
	v_mfma_f32_32x32x16_bf16 v[112:127], v[242:245], v[160:163], v[112:127]
	s_waitcnt lgkmcnt(0)
	v_mfma_f32_32x32x16_bf16 v[64:79], v[200:203], v[184:187], v[64:79]
	v_mfma_f32_32x32x16_bf16 v[80:95], v[242:245], v[184:187], v[80:95]
	s_waitcnt vmcnt(2)
	s_barrier
	ds_read_b128 v[188:191], v232 offset:49152
	ds_read_b128 v[204:207], v232 offset:53248
	ds_read_b128 v[192:195], v233 offset:49152
	ds_read_b128 v[208:211], v233 offset:53248
	ds_read_b128 v[196:199], v237 offset:49152
	ds_read_b128 v[238:241], v237 offset:53248
	ds_read_b128 v[200:203], v252 offset:49152
	ds_read_b128 v[242:245], v252 offset:53248
	s_waitcnt lgkmcnt(7)
	v_mfma_f32_32x32x16_bf16 v[32:47], v[188:191], v[140:143], v[32:47]
	v_lshl_add_u64 v[246:247], v[132:133], 0, s[50:51]
	s_add_i32 m0, s10, 0x8000
	s_nop 0
	global_load_lds_dwordx4 v[246:247], off
	s_waitcnt lgkmcnt(6)
	v_mfma_f32_32x32x16_bf16 v[48:63], v[204:207], v[140:143], v[48:63]
	v_lshl_add_u64 v[248:249], v[134:135], 0, s[50:51]
	s_add_i32 m0, s10, 0x8400
	s_nop 0
	global_load_lds_dwordx4 v[248:249], off
	v_mfma_f32_32x32x16_bf16 v[0:15], v[188:191], v[164:167], v[0:15]
	v_lshl_add_u64 v[246:247], v[132:133], 0, s[50:51]
	v_lshl_add_u64 v[246:247], v[246:247], 0, s[54:55]
	s_add_i32 m0, s10, 0x8800
	s_nop 0
	global_load_lds_dwordx4 v[246:247], off
	v_mfma_f32_32x32x16_bf16 v[16:31], v[204:207], v[164:167], v[16:31]
	v_lshl_add_u64 v[248:249], v[134:135], 0, s[50:51]
	v_lshl_add_u64 v[248:249], v[248:249], 0, s[54:55]
	s_add_i32 m0, s10, 0x8c00
	s_nop 0
	global_load_lds_dwordx4 v[248:249], off
	s_waitcnt lgkmcnt(5)
	v_mfma_f32_32x32x16_bf16 v[32:47], v[192:195], v[144:147], v[32:47]
	v_lshl_add_u64 v[246:247], v[128:129], 0, s[50:51]
	v_lshl_add_u64 v[246:247], v[246:247], 0, s[52:53]
	s_add_i32 m0, s63, 0x6000
	s_nop 0
	global_load_lds_dwordx4 v[246:247], off
	s_waitcnt lgkmcnt(4)
	v_mfma_f32_32x32x16_bf16 v[48:63], v[208:211], v[144:147], v[48:63]
	v_lshl_add_u64 v[248:249], v[130:131], 0, s[50:51]
	v_lshl_add_u64 v[248:249], v[248:249], 0, s[52:53]
	s_add_i32 m0, s63, 0x6400
	s_nop 0
	global_load_lds_dwordx4 v[248:249], off
	s_add_u32 s48, s48, 0x80
	s_addc_u32 s49, s49, 0
	s_add_u32 s50, s50, 0x80
	s_addc_u32 s51, s51, 0
	v_mfma_f32_32x32x16_bf16 v[0:15], v[192:195], v[170:173], v[0:15]
	v_mfma_f32_32x32x16_bf16 v[16:31], v[208:211], v[170:173], v[16:31]
	s_waitcnt lgkmcnt(3)
	v_mfma_f32_32x32x16_bf16 v[32:47], v[196:199], v[148:151], v[32:47]
	s_waitcnt lgkmcnt(2)
	v_mfma_f32_32x32x16_bf16 v[48:63], v[238:241], v[148:151], v[48:63]
	v_mfma_f32_32x32x16_bf16 v[0:15], v[196:199], v[180:183], v[0:15]
	v_mfma_f32_32x32x16_bf16 v[16:31], v[238:241], v[180:183], v[16:31]
	s_waitcnt lgkmcnt(1)
	v_mfma_f32_32x32x16_bf16 v[32:47], v[200:203], v[160:163], v[32:47]
	s_waitcnt lgkmcnt(0)
	v_mfma_f32_32x32x16_bf16 v[48:63], v[242:245], v[160:163], v[48:63]
	v_mfma_f32_32x32x16_bf16 v[0:15], v[200:203], v[184:187], v[0:15]
	v_mfma_f32_32x32x16_bf16 v[16:31], v[242:245], v[184:187], v[16:31]
	s_waitcnt vmcnt(0)
	s_barrier
	ds_read_b128 v[140:143], v136 offset:16384
	ds_read_b128 v[188:191], v232 offset:32768
	ds_read_b128 v[204:207], v232 offset:36864
	ds_read_b128 v[164:167], v136 offset:20480
	ds_read_b128 v[144:147], v137 offset:16384
	ds_read_b128 v[192:195], v233 offset:32768
	ds_read_b128 v[208:211], v233 offset:36864
	ds_read_b128 v[170:173], v137 offset:20480
	s_waitcnt lgkmcnt(6)
	v_mfma_f32_32x32x16_bf16 v[96:111], v[188:191], v[140:143], v[96:111]
	v_lshl_add_u64 v[246:247], v[132:133], 0, s[48:49]
	v_lshl_add_u64 v[246:247], v[246:247], 0, s[52:53]
	s_add_i32 m0, s10, 0xc000
	s_nop 0
	global_load_lds_dwordx4 v[246:247], off
	s_waitcnt lgkmcnt(5)
	v_mfma_f32_32x32x16_bf16 v[112:127], v[204:207], v[140:143], v[112:127]
	v_lshl_add_u64 v[248:249], v[134:135], 0, s[48:49]
	v_lshl_add_u64 v[248:249], v[248:249], 0, s[52:53]
	s_add_i32 m0, s10, 0xc400
	s_nop 0
	global_load_lds_dwordx4 v[248:249], off
	s_waitcnt lgkmcnt(4)
	v_mfma_f32_32x32x16_bf16 v[64:79], v[188:191], v[164:167], v[64:79]
	v_lshl_add_u64 v[246:247], v[132:133], 0, s[48:49]
	v_lshl_add_u64 v[246:247], v[246:247], 0, s[52:53]
	v_lshl_add_u64 v[246:247], v[246:247], 0, s[54:55]
	s_add_i32 m0, s10, 0xc800
	s_nop 0
	global_load_lds_dwordx4 v[246:247], off
	v_mfma_f32_32x32x16_bf16 v[80:95], v[204:207], v[164:167], v[80:95]
	v_lshl_add_u64 v[248:249], v[134:135], 0, s[48:49]
	v_lshl_add_u64 v[248:249], v[248:249], 0, s[52:53]
	v_lshl_add_u64 v[248:249], v[248:249], 0, s[54:55]
	s_add_i32 m0, s10, 0xcc00
	s_nop 0
	global_load_lds_dwordx4 v[248:249], off
	ds_read_b128 v[148:151], v138 offset:16384
	ds_read_b128 v[196:199], v237 offset:32768
	ds_read_b128 v[238:241], v237 offset:36864
	ds_read_b128 v[180:183], v138 offset:20480
	s_waitcnt lgkmcnt(6)
	v_mfma_f32_32x32x16_bf16 v[96:111], v[192:195], v[144:147], v[96:111]
	s_waitcnt lgkmcnt(5)
	v_mfma_f32_32x32x16_bf16 v[112:127], v[208:211], v[144:147], v[112:127]
	s_waitcnt lgkmcnt(4)
	v_mfma_f32_32x32x16_bf16 v[64:79], v[192:195], v[170:173], v[64:79]
	v_mfma_f32_32x32x16_bf16 v[80:95], v[208:211], v[170:173], v[80:95]
	ds_read_b128 v[160:163], v139 offset:16384
	ds_read_b128 v[200:203], v252 offset:32768
	ds_read_b128 v[242:245], v252 offset:36864
	ds_read_b128 v[184:187], v139 offset:20480
	s_waitcnt lgkmcnt(6)
	v_mfma_f32_32x32x16_bf16 v[96:111], v[196:199], v[148:151], v[96:111]
	s_waitcnt lgkmcnt(5)
	v_mfma_f32_32x32x16_bf16 v[112:127], v[238:241], v[148:151], v[112:127]
	s_waitcnt lgkmcnt(4)
	v_mfma_f32_32x32x16_bf16 v[64:79], v[196:199], v[180:183], v[64:79]
	v_mfma_f32_32x32x16_bf16 v[80:95], v[238:241], v[180:183], v[80:95]
	s_waitcnt lgkmcnt(2)
	v_mfma_f32_32x32x16_bf16 v[96:111], v[200:203], v[160:163], v[96:111]
	s_waitcnt lgkmcnt(1)
	v_mfma_f32_32x32x16_bf16 v[112:127], v[242:245], v[160:163], v[112:127]
	s_waitcnt lgkmcnt(0)
	v_mfma_f32_32x32x16_bf16 v[64:79], v[200:203], v[184:187], v[64:79]
	v_mfma_f32_32x32x16_bf16 v[80:95], v[242:245], v[184:187], v[80:95]
	s_waitcnt vmcnt(0)
	s_barrier
	ds_read_b128 v[188:191], v232 offset:49152
	ds_read_b128 v[204:207], v232 offset:53248
	ds_read_b128 v[192:195], v233 offset:49152
	ds_read_b128 v[208:211], v233 offset:53248
	ds_read_b128 v[196:199], v237 offset:49152
	ds_read_b128 v[238:241], v237 offset:53248
	ds_read_b128 v[200:203], v252 offset:49152
	ds_read_b128 v[242:245], v252 offset:53248
	s_waitcnt lgkmcnt(7)
	v_mfma_f32_32x32x16_bf16 v[32:47], v[188:191], v[140:143], v[32:47]
	s_waitcnt lgkmcnt(6)
	v_mfma_f32_32x32x16_bf16 v[48:63], v[204:207], v[140:143], v[48:63]
	v_mfma_f32_32x32x16_bf16 v[0:15], v[188:191], v[164:167], v[0:15]
	v_mfma_f32_32x32x16_bf16 v[16:31], v[204:207], v[164:167], v[16:31]
	s_waitcnt lgkmcnt(5)
	v_mfma_f32_32x32x16_bf16 v[32:47], v[192:195], v[144:147], v[32:47]
	s_waitcnt lgkmcnt(4)
	v_mfma_f32_32x32x16_bf16 v[48:63], v[208:211], v[144:147], v[48:63]
	v_mfma_f32_32x32x16_bf16 v[0:15], v[192:195], v[170:173], v[0:15]
	v_mfma_f32_32x32x16_bf16 v[16:31], v[208:211], v[170:173], v[16:31]
	s_waitcnt lgkmcnt(3)
	v_mfma_f32_32x32x16_bf16 v[32:47], v[196:199], v[148:151], v[32:47]
	s_waitcnt lgkmcnt(2)
	v_mfma_f32_32x32x16_bf16 v[48:63], v[238:241], v[148:151], v[48:63]
	v_mfma_f32_32x32x16_bf16 v[0:15], v[196:199], v[180:183], v[0:15]
	v_mfma_f32_32x32x16_bf16 v[16:31], v[238:241], v[180:183], v[16:31]
	s_waitcnt lgkmcnt(1)
	v_mfma_f32_32x32x16_bf16 v[32:47], v[200:203], v[160:163], v[32:47]
	s_waitcnt lgkmcnt(0)
	v_mfma_f32_32x32x16_bf16 v[48:63], v[242:245], v[160:163], v[48:63]
	v_mfma_f32_32x32x16_bf16 v[0:15], v[200:203], v[184:187], v[0:15]
	v_mfma_f32_32x32x16_bf16 v[16:31], v[242:245], v[184:187], v[16:31]
	s_branch .LBB0_770
